# extra priority flips every 8 MFMAs inside GEMM compute segments
# baseline (speedup 1.0000x reference)
.LBB0_22:
	s_add_u32 s18, s6, 0xfff80080
	s_addc_u32 s19, s7, -1
	s_add_i32 s41, 0, 0x10000
	s_cmp_eq_u32 s40, 28
	s_cselect_b32 s21, s13, s19
	s_cselect_b32 s20, s36, s18
	s_cselect_b32 s19, s11, s39
	s_cselect_b32 s18, s37, s38
	s_add_i32 s44, 0, 0x14000
	v_add_u32_e32 v140, s41, v175
	v_add_u32_e32 v166, s44, v175
	ds_read_b128 v[128:131], v140
	ds_read_b128 v[132:135], v140 offset:1024
	ds_read_b128 v[136:139], v140 offset:2048
	ds_read_b128 v[140:143], v140 offset:3072
	ds_read_b128 v[154:157], v166
	ds_read_b128 v[158:161], v166 offset:1024
	ds_read_b128 v[162:165], v166 offset:2048
	ds_read_b128 v[166:169], v166 offset:3072
	v_lshl_add_u64 v[170:171], s[6:7], 0, v[152:153]
	s_add_i32 m0, s25, 0xc000
	ds_read_b128 v[188:191], v186
	ds_read_b128 v[192:195], v186 offset:1024
	ds_read_b128 v[196:199], v186 offset:2048
	ds_read_b128 v[200:203], v186 offset:3072
	ds_read_b128 v[204:207], v186 offset:4096
	ds_read_b128 v[208:211], v186 offset:5120
	ds_read_b128 v[212:215], v186 offset:6144
	ds_read_b128 v[216:219], v186 offset:7168
	global_load_lds_dwordx4 v[170:171], off
	v_lshl_add_u64 v[170:171], s[6:7], 0, v[150:151]
	s_add_i32 m0, s25, 0xe000
	s_nop 0
	global_load_lds_dwordx4 v[170:171], off
	s_waitcnt vmcnt(8)
	s_waitcnt lgkmcnt(0)
	s_setprio 1
	s_barrier
	v_mfma_f32_16x16x32_bf16 v[124:127], v[128:131], v[188:191], v[124:127]
	v_mfma_f32_16x16x32_bf16 v[116:119], v[136:139], v[188:191], v[116:119]
	v_mfma_f32_16x16x32_bf16 v[108:111], v[128:131], v[196:199], v[108:111]
	v_mfma_f32_16x16x32_bf16 v[100:103], v[136:139], v[196:199], v[100:103]
	v_mfma_f32_16x16x32_bf16 v[92:95], v[128:131], v[204:207], v[92:95]
	v_mfma_f32_16x16x32_bf16 v[84:87], v[136:139], v[204:207], v[84:87]
	v_mfma_f32_16x16x32_bf16 v[76:79], v[128:131], v[212:215], v[76:79]
	v_mfma_f32_16x16x32_bf16 v[68:71], v[136:139], v[212:215], v[68:71]
	s_setprio 0
	s_setprio 1
	v_mfma_f32_16x16x32_bf16 v[124:127], v[132:135], v[192:195], v[124:127]
	v_mfma_f32_16x16x32_bf16 v[116:119], v[140:143], v[192:195], v[116:119]
	v_mfma_f32_16x16x32_bf16 v[108:111], v[132:135], v[200:203], v[108:111]
	v_mfma_f32_16x16x32_bf16 v[100:103], v[140:143], v[200:203], v[100:103]
	v_mfma_f32_16x16x32_bf16 v[92:95], v[132:135], v[208:211], v[92:95]
	v_mfma_f32_16x16x32_bf16 v[84:87], v[140:143], v[208:211], v[84:87]
	v_mfma_f32_16x16x32_bf16 v[76:79], v[132:135], v[216:219], v[76:79]
	v_mfma_f32_16x16x32_bf16 v[68:71], v[140:143], v[216:219], v[68:71]
	s_setprio 0
	s_setprio 1
	v_mfma_f32_16x16x32_bf16 v[120:123], v[154:157], v[188:191], v[120:123]
	v_mfma_f32_16x16x32_bf16 v[112:115], v[162:165], v[188:191], v[112:115]
	v_mfma_f32_16x16x32_bf16 v[104:107], v[154:157], v[196:199], v[104:107]
	v_mfma_f32_16x16x32_bf16 v[96:99], v[162:165], v[196:199], v[96:99]
	v_mfma_f32_16x16x32_bf16 v[88:91], v[154:157], v[204:207], v[88:91]
	v_mfma_f32_16x16x32_bf16 v[80:83], v[162:165], v[204:207], v[80:83]
	v_mfma_f32_16x16x32_bf16 v[72:75], v[154:157], v[212:215], v[72:75]
	v_mfma_f32_16x16x32_bf16 v[64:67], v[162:165], v[212:215], v[64:67]
	s_setprio 0
	s_setprio 1
	v_mfma_f32_16x16x32_bf16 v[120:123], v[158:161], v[192:195], v[120:123]
	v_mfma_f32_16x16x32_bf16 v[112:115], v[166:169], v[192:195], v[112:115]
	v_mfma_f32_16x16x32_bf16 v[104:107], v[158:161], v[200:203], v[104:107]
	v_mfma_f32_16x16x32_bf16 v[96:99], v[166:169], v[200:203], v[96:99]
	v_mfma_f32_16x16x32_bf16 v[88:91], v[158:161], v[208:211], v[88:91]
	v_mfma_f32_16x16x32_bf16 v[80:83], v[166:169], v[208:211], v[80:83]
	v_mfma_f32_16x16x32_bf16 v[72:75], v[158:161], v[216:219], v[72:75]
	v_mfma_f32_16x16x32_bf16 v[64:67], v[166:169], v[216:219], v[64:67]
	s_barrier
	s_setprio 0
	s_add_i32 s41, s41, s24
	v_lshl_add_u64 v[170:171], s[18:19], 0, v[146:147]
	s_mov_b32 m0, s41
	ds_read_b128 v[188:191], v186 offset:16384
	ds_read_b128 v[192:195], v186 offset:17408
	ds_read_b128 v[196:199], v186 offset:18432
	ds_read_b128 v[200:203], v186 offset:19456
	ds_read_b128 v[204:207], v186 offset:20480
	ds_read_b128 v[208:211], v186 offset:21504
	ds_read_b128 v[212:215], v186 offset:22528
	ds_read_b128 v[216:219], v186 offset:23552
	global_load_lds_dwordx4 v[170:171], off
	s_add_i32 m0, s41, 0x2000
	s_add_u32 s42, s18, 0x80000
	v_lshl_add_u64 v[228:229], s[18:19], 0, v[144:145]
	s_addc_u32 s43, s19, 0
	s_add_i32 s41, s44, s24
	global_load_lds_dwordx4 v[228:229], off
	v_lshl_add_u64 v[230:231], s[42:43], 0, v[146:147]
	s_mov_b32 m0, s41
	v_lshl_add_u64 v[236:237], s[20:21], 0, v[144:145]
	global_load_lds_dwordx4 v[230:231], off
	v_lshl_add_u64 v[230:231], s[42:43], 0, v[144:145]
	s_add_i32 m0, s41, 0x2000
	s_nop 0
	global_load_lds_dwordx4 v[230:231], off
	v_lshl_add_u64 v[230:231], s[20:21], 0, v[146:147]
	s_mov_b32 m0, s25
	s_nop 0
	global_load_lds_dwordx4 v[230:231], off
	s_mov_b32 m0, s26
	s_nop 0
	global_load_lds_dwordx4 v[236:237], off
	s_waitcnt vmcnt(8)
	s_waitcnt lgkmcnt(0)
	s_setprio 1
	s_barrier
	v_mfma_f32_16x16x32_bf16 v[60:63], v[128:131], v[188:191], v[60:63]
	v_mfma_f32_16x16x32_bf16 v[52:55], v[136:139], v[188:191], v[52:55]
	v_mfma_f32_16x16x32_bf16 v[44:47], v[128:131], v[196:199], v[44:47]
	v_mfma_f32_16x16x32_bf16 v[36:39], v[136:139], v[196:199], v[36:39]
	v_mfma_f32_16x16x32_bf16 v[28:31], v[128:131], v[204:207], v[28:31]
	v_mfma_f32_16x16x32_bf16 v[20:23], v[136:139], v[204:207], v[20:23]
	v_mfma_f32_16x16x32_bf16 v[12:15], v[128:131], v[212:215], v[12:15]
	v_mfma_f32_16x16x32_bf16 v[4:7], v[136:139], v[212:215], v[4:7]
	s_setprio 0
	s_setprio 1
	v_mfma_f32_16x16x32_bf16 v[60:63], v[132:135], v[192:195], v[60:63]
	v_mfma_f32_16x16x32_bf16 v[52:55], v[140:143], v[192:195], v[52:55]
	v_mfma_f32_16x16x32_bf16 v[44:47], v[132:135], v[200:203], v[44:47]
	v_mfma_f32_16x16x32_bf16 v[36:39], v[140:143], v[200:203], v[36:39]
	v_mfma_f32_16x16x32_bf16 v[28:31], v[132:135], v[208:211], v[28:31]
	v_mfma_f32_16x16x32_bf16 v[20:23], v[140:143], v[208:211], v[20:23]
	v_mfma_f32_16x16x32_bf16 v[12:15], v[132:135], v[216:219], v[12:15]
	v_mfma_f32_16x16x32_bf16 v[4:7], v[140:143], v[216:219], v[4:7]
	s_setprio 0
	s_setprio 1
	v_mfma_f32_16x16x32_bf16 v[56:59], v[154:157], v[188:191], v[56:59]
	v_mfma_f32_16x16x32_bf16 v[48:51], v[162:165], v[188:191], v[48:51]
	v_mfma_f32_16x16x32_bf16 v[40:43], v[154:157], v[196:199], v[40:43]
	v_mfma_f32_16x16x32_bf16 v[32:35], v[162:165], v[196:199], v[32:35]
	v_mfma_f32_16x16x32_bf16 v[24:27], v[154:157], v[204:207], v[24:27]
	v_mfma_f32_16x16x32_bf16 v[16:19], v[162:165], v[204:207], v[16:19]
	v_mfma_f32_16x16x32_bf16 v[8:11], v[154:157], v[212:215], v[8:11]
	v_mfma_f32_16x16x32_bf16 v[0:3], v[162:165], v[212:215], v[0:3]
	s_setprio 0
	s_setprio 1
	v_mfma_f32_16x16x32_bf16 v[56:59], v[158:161], v[192:195], v[56:59]
	v_mfma_f32_16x16x32_bf16 v[48:51], v[166:169], v[192:195], v[48:51]
	v_mfma_f32_16x16x32_bf16 v[40:43], v[158:161], v[200:203], v[40:43]
	v_mfma_f32_16x16x32_bf16 v[32:35], v[166:169], v[200:203], v[32:35]
	v_mfma_f32_16x16x32_bf16 v[24:27], v[158:161], v[208:211], v[24:27]
	v_mfma_f32_16x16x32_bf16 v[16:19], v[166:169], v[208:211], v[16:19]
	v_mfma_f32_16x16x32_bf16 v[8:11], v[158:161], v[216:219], v[8:11]
	v_mfma_f32_16x16x32_bf16 v[0:3], v[166:169], v[216:219], v[0:3]
	s_barrier
	s_setprio 0
	s_add_i32 s41, 0, 0x18000
	s_add_i32 s42, 0, 0x1c000
	v_add_u32_e32 v140, s41, v175
	v_add_u32_e32 v166, s42, v175
	ds_read_b128 v[128:131], v140
	ds_read_b128 v[132:135], v140 offset:1024
	ds_read_b128 v[136:139], v140 offset:2048
	ds_read_b128 v[140:143], v140 offset:3072
	ds_read_b128 v[154:157], v166
	ds_read_b128 v[158:161], v166 offset:1024
	ds_read_b128 v[162:165], v166 offset:2048
	ds_read_b128 v[166:169], v166 offset:3072
	s_add_u32 s20, s20, 0x80000
	s_addc_u32 s21, s21, 0
	s_mov_b32 m0, s27
	v_lshl_add_u64 v[238:239], s[20:21], 0, v[146:147]
	ds_read_b128 v[188:191], v186 offset:32768
	ds_read_b128 v[192:195], v186 offset:33792
	ds_read_b128 v[196:199], v186 offset:34816
	ds_read_b128 v[200:203], v186 offset:35840
	ds_read_b128 v[204:207], v186 offset:36864
	ds_read_b128 v[208:211], v186 offset:37888
	ds_read_b128 v[212:215], v186 offset:38912
	ds_read_b128 v[216:219], v186 offset:39936
	global_load_lds_dwordx4 v[238:239], off
	v_lshl_add_u64 v[238:239], s[20:21], 0, v[144:145]
	s_mov_b32 m0, s28
	s_nop 0
	global_load_lds_dwordx4 v[238:239], off
	s_waitcnt vmcnt(8)
	s_waitcnt lgkmcnt(0)
	s_setprio 1
	s_barrier
	v_mfma_f32_16x16x32_bf16 v[124:127], v[128:131], v[188:191], v[124:127]
	v_mfma_f32_16x16x32_bf16 v[116:119], v[136:139], v[188:191], v[116:119]
	v_mfma_f32_16x16x32_bf16 v[108:111], v[128:131], v[196:199], v[108:111]
	v_mfma_f32_16x16x32_bf16 v[100:103], v[136:139], v[196:199], v[100:103]
	v_mfma_f32_16x16x32_bf16 v[92:95], v[128:131], v[204:207], v[92:95]
	v_mfma_f32_16x16x32_bf16 v[84:87], v[136:139], v[204:207], v[84:87]
	v_mfma_f32_16x16x32_bf16 v[76:79], v[128:131], v[212:215], v[76:79]
	v_mfma_f32_16x16x32_bf16 v[68:71], v[136:139], v[212:215], v[68:71]
	s_setprio 0
	s_setprio 1
	v_mfma_f32_16x16x32_bf16 v[124:127], v[132:135], v[192:195], v[124:127]
	v_mfma_f32_16x16x32_bf16 v[116:119], v[140:143], v[192:195], v[116:119]
	v_mfma_f32_16x16x32_bf16 v[108:111], v[132:135], v[200:203], v[108:111]
	v_mfma_f32_16x16x32_bf16 v[100:103], v[140:143], v[200:203], v[100:103]
	v_mfma_f32_16x16x32_bf16 v[92:95], v[132:135], v[208:211], v[92:95]
	v_mfma_f32_16x16x32_bf16 v[84:87], v[140:143], v[208:211], v[84:87]
	v_mfma_f32_16x16x32_bf16 v[76:79], v[132:135], v[216:219], v[76:79]
	v_mfma_f32_16x16x32_bf16 v[68:71], v[140:143], v[216:219], v[68:71]
	s_setprio 0
	s_setprio 1
	v_mfma_f32_16x16x32_bf16 v[120:123], v[154:157], v[188:191], v[120:123]
	v_mfma_f32_16x16x32_bf16 v[112:115], v[162:165], v[188:191], v[112:115]
	v_mfma_f32_16x16x32_bf16 v[104:107], v[154:157], v[196:199], v[104:107]
	v_mfma_f32_16x16x32_bf16 v[96:99], v[162:165], v[196:199], v[96:99]
	v_mfma_f32_16x16x32_bf16 v[88:91], v[154:157], v[204:207], v[88:91]
	v_mfma_f32_16x16x32_bf16 v[80:83], v[162:165], v[204:207], v[80:83]
	v_mfma_f32_16x16x32_bf16 v[72:75], v[154:157], v[212:215], v[72:75]
	v_mfma_f32_16x16x32_bf16 v[64:67], v[162:165], v[212:215], v[64:67]
	s_setprio 0
	s_setprio 1
	v_mfma_f32_16x16x32_bf16 v[120:123], v[158:161], v[192:195], v[120:123]
	v_mfma_f32_16x16x32_bf16 v[112:115], v[166:169], v[192:195], v[112:115]
	v_mfma_f32_16x16x32_bf16 v[104:107], v[158:161], v[200:203], v[104:107]
	v_mfma_f32_16x16x32_bf16 v[96:99], v[166:169], v[200:203], v[96:99]
	v_mfma_f32_16x16x32_bf16 v[88:91], v[158:161], v[208:211], v[88:91]
	v_mfma_f32_16x16x32_bf16 v[80:83], v[166:169], v[208:211], v[80:83]
	v_mfma_f32_16x16x32_bf16 v[72:75], v[158:161], v[216:219], v[72:75]
	v_mfma_f32_16x16x32_bf16 v[64:67], v[166:169], v[216:219], v[64:67]
	s_barrier
	s_setprio 0
	s_add_i32 s20, s41, s24
	v_lshl_add_u64 v[170:171], v[170:171], 0, s[0:1]
	s_mov_b32 m0, s20
	ds_read_b128 v[188:191], v186 offset:49152
	ds_read_b128 v[192:195], v186 offset:50176
	ds_read_b128 v[196:199], v186 offset:51200
	ds_read_b128 v[200:203], v186 offset:52224
	ds_read_b128 v[204:207], v186 offset:53248
	ds_read_b128 v[208:211], v186 offset:54272
	ds_read_b128 v[212:215], v186 offset:55296
	ds_read_b128 v[216:219], v186 offset:56320
	global_load_lds_dwordx4 v[170:171], off
	s_add_i32 m0, s20, 0x2000
	s_add_u32 s18, s18, 0x80080
	v_lshl_add_u64 v[170:171], v[228:229], 0, s[0:1]
	s_addc_u32 s19, s19, 0
	s_add_i32 s20, s42, s24
	global_load_lds_dwordx4 v[170:171], off
	v_lshl_add_u64 v[170:171], s[18:19], 0, v[146:147]
	s_mov_b32 m0, s20
	s_nop 0
	global_load_lds_dwordx4 v[170:171], off
	v_lshl_add_u64 v[170:171], s[18:19], 0, v[144:145]
	s_add_i32 m0, s20, 0x2000
	s_nop 0
	global_load_lds_dwordx4 v[170:171], off
	v_lshl_add_u64 v[170:171], v[230:231], 0, s[0:1]
	s_mov_b32 m0, s29
	s_nop 0
	global_load_lds_dwordx4 v[170:171], off
	v_lshl_add_u64 v[170:171], v[236:237], 0, s[0:1]
	s_mov_b32 m0, s30
	s_nop 0
	global_load_lds_dwordx4 v[170:171], off
	s_waitcnt vmcnt(8)
	s_waitcnt lgkmcnt(0)
	s_setprio 1
	s_barrier
	v_mfma_f32_16x16x32_bf16 v[60:63], v[128:131], v[188:191], v[60:63]
	v_mfma_f32_16x16x32_bf16 v[52:55], v[136:139], v[188:191], v[52:55]
	v_mfma_f32_16x16x32_bf16 v[44:47], v[128:131], v[196:199], v[44:47]
	v_mfma_f32_16x16x32_bf16 v[36:39], v[136:139], v[196:199], v[36:39]
	v_mfma_f32_16x16x32_bf16 v[28:31], v[128:131], v[204:207], v[28:31]
	v_mfma_f32_16x16x32_bf16 v[20:23], v[136:139], v[204:207], v[20:23]
	v_mfma_f32_16x16x32_bf16 v[12:15], v[128:131], v[212:215], v[12:15]
	v_mfma_f32_16x16x32_bf16 v[4:7], v[136:139], v[212:215], v[4:7]
	s_setprio 0
	s_setprio 1
	v_mfma_f32_16x16x32_bf16 v[60:63], v[132:135], v[192:195], v[60:63]
	v_mfma_f32_16x16x32_bf16 v[52:55], v[140:143], v[192:195], v[52:55]
	v_mfma_f32_16x16x32_bf16 v[44:47], v[132:135], v[200:203], v[44:47]
	v_mfma_f32_16x16x32_bf16 v[36:39], v[140:143], v[200:203], v[36:39]
	v_mfma_f32_16x16x32_bf16 v[28:31], v[132:135], v[208:211], v[28:31]
	v_mfma_f32_16x16x32_bf16 v[20:23], v[140:143], v[208:211], v[20:23]
	v_mfma_f32_16x16x32_bf16 v[12:15], v[132:135], v[216:219], v[12:15]
	v_mfma_f32_16x16x32_bf16 v[4:7], v[140:143], v[216:219], v[4:7]
	s_setprio 0
	s_setprio 1
	v_mfma_f32_16x16x32_bf16 v[56:59], v[154:157], v[188:191], v[56:59]
	v_mfma_f32_16x16x32_bf16 v[48:51], v[162:165], v[188:191], v[48:51]
	v_mfma_f32_16x16x32_bf16 v[40:43], v[154:157], v[196:199], v[40:43]
	v_mfma_f32_16x16x32_bf16 v[32:35], v[162:165], v[196:199], v[32:35]
	v_mfma_f32_16x16x32_bf16 v[24:27], v[154:157], v[204:207], v[24:27]
	v_mfma_f32_16x16x32_bf16 v[16:19], v[162:165], v[204:207], v[16:19]
	v_mfma_f32_16x16x32_bf16 v[8:11], v[154:157], v[212:215], v[8:11]
	v_mfma_f32_16x16x32_bf16 v[0:3], v[162:165], v[212:215], v[0:3]
	s_setprio 0
	s_setprio 1
	v_mfma_f32_16x16x32_bf16 v[56:59], v[158:161], v[192:195], v[56:59]
	v_mfma_f32_16x16x32_bf16 v[48:51], v[166:169], v[192:195], v[48:51]
	v_mfma_f32_16x16x32_bf16 v[40:43], v[158:161], v[200:203], v[40:43]
	v_mfma_f32_16x16x32_bf16 v[32:35], v[166:169], v[200:203], v[32:35]
	v_mfma_f32_16x16x32_bf16 v[24:27], v[158:161], v[208:211], v[24:27]
	v_mfma_f32_16x16x32_bf16 v[16:19], v[166:169], v[208:211], v[16:19]
	v_mfma_f32_16x16x32_bf16 v[8:11], v[158:161], v[216:219], v[8:11]
	v_mfma_f32_16x16x32_bf16 v[0:3], v[166:169], v[216:219], v[0:3]
	s_barrier
	s_setprio 0
	s_add_i32 s40, s40, 2
	s_add_u32 s38, s38, 0x100
	s_addc_u32 s39, s39, 0
	s_add_u32 s6, s6, 0x100
	s_addc_u32 s7, s7, 0
	s_cmp_gt_u32 s40, 29
	s_cbranch_scc0 .LBB0_22
	s_and_b64 vcc, exec, s[8:9]
	s_cbranch_vccz .LBB0_25
	s_barrier

.LBB0_50:
	s_add_u32 s24, s2, 0x100
	s_addc_u32 s25, s3, 0
	s_add_i32 s52, 0, 0x10000
	s_cmp_eq_u32 s51, 28
	s_cselect_b32 s29, s19, s25
	s_cselect_b32 s28, s47, s24
	s_cselect_b32 s27, s17, s50
	s_cselect_b32 s26, s48, s49
	s_add_i32 s53, 0, 0x14000
	v_add_u32_e32 v140, s52, v236
	v_add_u32_e32 v156, s53, v236
	s_waitcnt lgkmcnt(0)
	ds_read_b128 v[128:131], v140
	ds_read_b128 v[132:135], v140 offset:1024
	ds_read_b128 v[136:139], v140 offset:2048
	ds_read_b128 v[140:143], v140 offset:3072
	ds_read_b128 v[144:147], v156
	ds_read_b128 v[148:151], v156 offset:1024
	ds_read_b128 v[152:155], v156 offset:2048
	ds_read_b128 v[156:159], v156 offset:3072
	v_lshl_add_u64 v[208:209], s[2:3], 0, v[190:191]
	s_add_i32 m0, s37, 0xc000
	ds_read_b128 v[160:163], v238
	ds_read_b128 v[164:167], v238 offset:1024
	ds_read_b128 v[168:171], v238 offset:2048
	ds_read_b128 v[172:175], v238 offset:3072
	ds_read_b128 v[192:195], v238 offset:4096
	ds_read_b128 v[196:199], v238 offset:5120
	ds_read_b128 v[200:203], v238 offset:6144
	ds_read_b128 v[204:207], v238 offset:7168
	global_load_lds_dwordx4 v[208:209], off
	v_lshl_add_u64 v[208:209], s[2:3], 0, v[188:189]
	s_add_i32 m0, s37, 0xe000
	s_nop 0
	global_load_lds_dwordx4 v[208:209], off
	s_waitcnt vmcnt(8)
	s_waitcnt lgkmcnt(0)
	s_setprio 1
	s_barrier
	v_mfma_f32_16x16x32_bf16 v[124:127], v[128:131], v[160:163], v[124:127]
	v_mfma_f32_16x16x32_bf16 v[120:123], v[136:139], v[160:163], v[120:123]
	v_mfma_f32_16x16x32_bf16 v[108:111], v[128:131], v[168:171], v[108:111]
	v_mfma_f32_16x16x32_bf16 v[104:107], v[136:139], v[168:171], v[104:107]
	v_mfma_f32_16x16x32_bf16 v[92:95], v[128:131], v[192:195], v[92:95]
	v_mfma_f32_16x16x32_bf16 v[88:91], v[136:139], v[192:195], v[88:91]
	v_mfma_f32_16x16x32_bf16 v[76:79], v[128:131], v[200:203], v[76:79]
	v_mfma_f32_16x16x32_bf16 v[72:75], v[136:139], v[200:203], v[72:75]
	s_setprio 0
	s_setprio 1
	v_mfma_f32_16x16x32_bf16 v[124:127], v[132:135], v[164:167], v[124:127]
	v_mfma_f32_16x16x32_bf16 v[120:123], v[140:143], v[164:167], v[120:123]
	v_mfma_f32_16x16x32_bf16 v[108:111], v[132:135], v[172:175], v[108:111]
	v_mfma_f32_16x16x32_bf16 v[104:107], v[140:143], v[172:175], v[104:107]
	v_mfma_f32_16x16x32_bf16 v[92:95], v[132:135], v[196:199], v[92:95]
	v_mfma_f32_16x16x32_bf16 v[88:91], v[140:143], v[196:199], v[88:91]
	v_mfma_f32_16x16x32_bf16 v[76:79], v[132:135], v[204:207], v[76:79]
	v_mfma_f32_16x16x32_bf16 v[72:75], v[140:143], v[204:207], v[72:75]
	s_setprio 0
	s_setprio 1
	v_mfma_f32_16x16x32_bf16 v[116:119], v[144:147], v[160:163], v[116:119]
	v_mfma_f32_16x16x32_bf16 v[112:115], v[152:155], v[160:163], v[112:115]
	v_mfma_f32_16x16x32_bf16 v[100:103], v[144:147], v[168:171], v[100:103]
	v_mfma_f32_16x16x32_bf16 v[96:99], v[152:155], v[168:171], v[96:99]
	v_mfma_f32_16x16x32_bf16 v[84:87], v[144:147], v[192:195], v[84:87]
	v_mfma_f32_16x16x32_bf16 v[80:83], v[152:155], v[192:195], v[80:83]
	v_mfma_f32_16x16x32_bf16 v[68:71], v[144:147], v[200:203], v[68:71]
	v_mfma_f32_16x16x32_bf16 v[64:67], v[152:155], v[200:203], v[64:67]
	s_setprio 0
	s_setprio 1
	v_mfma_f32_16x16x32_bf16 v[116:119], v[148:151], v[164:167], v[116:119]
	v_mfma_f32_16x16x32_bf16 v[112:115], v[156:159], v[164:167], v[112:115]
	v_mfma_f32_16x16x32_bf16 v[100:103], v[148:151], v[172:175], v[100:103]
	v_mfma_f32_16x16x32_bf16 v[96:99], v[156:159], v[172:175], v[96:99]
	v_mfma_f32_16x16x32_bf16 v[84:87], v[148:151], v[196:199], v[84:87]
	v_mfma_f32_16x16x32_bf16 v[80:83], v[156:159], v[196:199], v[80:83]
	v_mfma_f32_16x16x32_bf16 v[68:71], v[148:151], v[204:207], v[68:71]
	v_mfma_f32_16x16x32_bf16 v[64:67], v[156:159], v[204:207], v[64:67]
	s_barrier
	s_setprio 0
	s_add_i32 s2, s52, s34
	v_lshl_add_u64 v[208:209], s[26:27], 0, v[176:177]
	s_mov_b32 m0, s2
	ds_read_b128 v[160:163], v238 offset:16384
	ds_read_b128 v[164:167], v238 offset:17408
	ds_read_b128 v[168:171], v238 offset:18432
	ds_read_b128 v[172:175], v238 offset:19456
	ds_read_b128 v[192:195], v238 offset:20480
	ds_read_b128 v[196:199], v238 offset:21504
	ds_read_b128 v[200:203], v238 offset:22528
	ds_read_b128 v[204:207], v238 offset:23552
	global_load_lds_dwordx4 v[208:209], off
	s_add_i32 m0, s2, 0x2000
	s_add_u32 s2, s26, 0x80000
	v_lshl_add_u64 v[210:211], s[26:27], 0, v[186:187]
	s_addc_u32 s3, s27, 0
	s_add_i32 s52, s53, s34
	global_load_lds_dwordx4 v[210:211], off
	v_lshl_add_u64 v[212:213], s[2:3], 0, v[176:177]
	s_mov_b32 m0, s52
	v_lshl_add_u64 v[214:215], s[28:29], 0, v[186:187]
	global_load_lds_dwordx4 v[212:213], off
	v_lshl_add_u64 v[212:213], s[2:3], 0, v[186:187]
	s_add_i32 m0, s52, 0x2000
	s_nop 0
	global_load_lds_dwordx4 v[212:213], off
	v_lshl_add_u64 v[212:213], s[28:29], 0, v[176:177]
	s_mov_b32 m0, s37
	s_nop 0
	global_load_lds_dwordx4 v[212:213], off
	s_mov_b32 m0, s38
	s_nop 0
	global_load_lds_dwordx4 v[214:215], off
	s_waitcnt vmcnt(8)
	s_waitcnt lgkmcnt(0)
	s_setprio 1
	s_barrier
	v_mfma_f32_16x16x32_bf16 v[60:63], v[128:131], v[160:163], v[60:63]
	v_mfma_f32_16x16x32_bf16 v[56:59], v[136:139], v[160:163], v[56:59]
	v_mfma_f32_16x16x32_bf16 v[44:47], v[128:131], v[168:171], v[44:47]
	v_mfma_f32_16x16x32_bf16 v[40:43], v[136:139], v[168:171], v[40:43]
	v_mfma_f32_16x16x32_bf16 v[28:31], v[128:131], v[192:195], v[28:31]
	v_mfma_f32_16x16x32_bf16 v[24:27], v[136:139], v[192:195], v[24:27]
	v_mfma_f32_16x16x32_bf16 v[12:15], v[128:131], v[200:203], v[12:15]
	v_mfma_f32_16x16x32_bf16 v[8:11], v[136:139], v[200:203], v[8:11]
	s_setprio 0
	s_setprio 1
	v_mfma_f32_16x16x32_bf16 v[60:63], v[132:135], v[164:167], v[60:63]
	v_mfma_f32_16x16x32_bf16 v[56:59], v[140:143], v[164:167], v[56:59]
	v_mfma_f32_16x16x32_bf16 v[44:47], v[132:135], v[172:175], v[44:47]
	v_mfma_f32_16x16x32_bf16 v[40:43], v[140:143], v[172:175], v[40:43]
	v_mfma_f32_16x16x32_bf16 v[28:31], v[132:135], v[196:199], v[28:31]
	v_mfma_f32_16x16x32_bf16 v[24:27], v[140:143], v[196:199], v[24:27]
	v_mfma_f32_16x16x32_bf16 v[12:15], v[132:135], v[204:207], v[12:15]
	v_mfma_f32_16x16x32_bf16 v[8:11], v[140:143], v[204:207], v[8:11]
	s_setprio 0
	s_setprio 1
	v_mfma_f32_16x16x32_bf16 v[52:55], v[144:147], v[160:163], v[52:55]
	v_mfma_f32_16x16x32_bf16 v[48:51], v[152:155], v[160:163], v[48:51]
	v_mfma_f32_16x16x32_bf16 v[36:39], v[144:147], v[168:171], v[36:39]
	v_mfma_f32_16x16x32_bf16 v[32:35], v[152:155], v[168:171], v[32:35]
	v_mfma_f32_16x16x32_bf16 v[20:23], v[144:147], v[192:195], v[20:23]
	v_mfma_f32_16x16x32_bf16 v[16:19], v[152:155], v[192:195], v[16:19]
	v_mfma_f32_16x16x32_bf16 v[4:7], v[144:147], v[200:203], v[4:7]
	v_mfma_f32_16x16x32_bf16 v[0:3], v[152:155], v[200:203], v[0:3]
	s_setprio 0
	s_setprio 1
	v_mfma_f32_16x16x32_bf16 v[52:55], v[148:151], v[164:167], v[52:55]
	v_mfma_f32_16x16x32_bf16 v[48:51], v[156:159], v[164:167], v[48:51]
	v_mfma_f32_16x16x32_bf16 v[36:39], v[148:151], v[172:175], v[36:39]
	v_mfma_f32_16x16x32_bf16 v[32:35], v[156:159], v[172:175], v[32:35]
	v_mfma_f32_16x16x32_bf16 v[20:23], v[148:151], v[196:199], v[20:23]
	v_mfma_f32_16x16x32_bf16 v[16:19], v[156:159], v[196:199], v[16:19]
	v_mfma_f32_16x16x32_bf16 v[4:7], v[148:151], v[204:207], v[4:7]
	v_mfma_f32_16x16x32_bf16 v[0:3], v[156:159], v[204:207], v[0:3]
	s_barrier
	s_setprio 0
	s_add_i32 s52, 0, 0x18000
	s_add_i32 s53, 0, 0x1c000
	v_add_u32_e32 v140, s52, v236
	v_add_u32_e32 v156, s53, v236
	ds_read_b128 v[128:131], v140
	ds_read_b128 v[132:135], v140 offset:1024
	ds_read_b128 v[136:139], v140 offset:2048
	ds_read_b128 v[140:143], v140 offset:3072
	ds_read_b128 v[144:147], v156
	ds_read_b128 v[148:151], v156 offset:1024
	ds_read_b128 v[152:155], v156 offset:2048
	ds_read_b128 v[156:159], v156 offset:3072
	s_add_u32 s2, s28, 0x80000
	s_addc_u32 s3, s29, 0
	s_mov_b32 m0, s39
	v_lshl_add_u64 v[216:217], s[2:3], 0, v[176:177]
	ds_read_b128 v[160:163], v238 offset:32768
	ds_read_b128 v[164:167], v238 offset:33792
	ds_read_b128 v[168:171], v238 offset:34816
	ds_read_b128 v[172:175], v238 offset:35840
	ds_read_b128 v[192:195], v238 offset:36864
	ds_read_b128 v[196:199], v238 offset:37888
	ds_read_b128 v[200:203], v238 offset:38912
	ds_read_b128 v[204:207], v238 offset:39936
	global_load_lds_dwordx4 v[216:217], off
	v_lshl_add_u64 v[216:217], s[2:3], 0, v[186:187]
	s_mov_b32 m0, s40
	s_nop 0
	global_load_lds_dwordx4 v[216:217], off
	s_waitcnt vmcnt(8)
	s_waitcnt lgkmcnt(0)
	s_setprio 1
	s_barrier
	v_mfma_f32_16x16x32_bf16 v[124:127], v[128:131], v[160:163], v[124:127]
	v_mfma_f32_16x16x32_bf16 v[120:123], v[136:139], v[160:163], v[120:123]
	v_mfma_f32_16x16x32_bf16 v[108:111], v[128:131], v[168:171], v[108:111]
	v_mfma_f32_16x16x32_bf16 v[104:107], v[136:139], v[168:171], v[104:107]
	v_mfma_f32_16x16x32_bf16 v[92:95], v[128:131], v[192:195], v[92:95]
	v_mfma_f32_16x16x32_bf16 v[88:91], v[136:139], v[192:195], v[88:91]
	v_mfma_f32_16x16x32_bf16 v[76:79], v[128:131], v[200:203], v[76:79]
	v_mfma_f32_16x16x32_bf16 v[72:75], v[136:139], v[200:203], v[72:75]
	s_setprio 0
	s_setprio 1
	v_mfma_f32_16x16x32_bf16 v[124:127], v[132:135], v[164:167], v[124:127]
	v_mfma_f32_16x16x32_bf16 v[120:123], v[140:143], v[164:167], v[120:123]
	v_mfma_f32_16x16x32_bf16 v[108:111], v[132:135], v[172:175], v[108:111]
	v_mfma_f32_16x16x32_bf16 v[104:107], v[140:143], v[172:175], v[104:107]
	v_mfma_f32_16x16x32_bf16 v[92:95], v[132:135], v[196:199], v[92:95]
	v_mfma_f32_16x16x32_bf16 v[88:91], v[140:143], v[196:199], v[88:91]
	v_mfma_f32_16x16x32_bf16 v[76:79], v[132:135], v[204:207], v[76:79]
	v_mfma_f32_16x16x32_bf16 v[72:75], v[140:143], v[204:207], v[72:75]
	s_setprio 0
	s_setprio 1
	v_mfma_f32_16x16x32_bf16 v[116:119], v[144:147], v[160:163], v[116:119]
	v_mfma_f32_16x16x32_bf16 v[112:115], v[152:155], v[160:163], v[112:115]
	v_mfma_f32_16x16x32_bf16 v[100:103], v[144:147], v[168:171], v[100:103]
	v_mfma_f32_16x16x32_bf16 v[96:99], v[152:155], v[168:171], v[96:99]
	v_mfma_f32_16x16x32_bf16 v[84:87], v[144:147], v[192:195], v[84:87]
	v_mfma_f32_16x16x32_bf16 v[80:83], v[152:155], v[192:195], v[80:83]
	v_mfma_f32_16x16x32_bf16 v[68:71], v[144:147], v[200:203], v[68:71]
	v_mfma_f32_16x16x32_bf16 v[64:67], v[152:155], v[200:203], v[64:67]
	s_setprio 0
	s_setprio 1
	v_mfma_f32_16x16x32_bf16 v[116:119], v[148:151], v[164:167], v[116:119]
	v_mfma_f32_16x16x32_bf16 v[112:115], v[156:159], v[164:167], v[112:115]
	v_mfma_f32_16x16x32_bf16 v[100:103], v[148:151], v[172:175], v[100:103]
	v_mfma_f32_16x16x32_bf16 v[96:99], v[156:159], v[172:175], v[96:99]
	v_mfma_f32_16x16x32_bf16 v[84:87], v[148:151], v[196:199], v[84:87]
	v_mfma_f32_16x16x32_bf16 v[80:83], v[156:159], v[196:199], v[80:83]
	v_mfma_f32_16x16x32_bf16 v[68:71], v[148:151], v[204:207], v[68:71]
	v_mfma_f32_16x16x32_bf16 v[64:67], v[156:159], v[204:207], v[64:67]
	s_barrier
	s_setprio 0
	s_add_i32 s2, s52, s34
	v_lshl_add_u64 v[208:209], v[208:209], 0, s[0:1]
	s_mov_b32 m0, s2
	ds_read_b128 v[160:163], v238 offset:49152
	ds_read_b128 v[164:167], v238 offset:50176
	ds_read_b128 v[168:171], v238 offset:51200
	ds_read_b128 v[172:175], v238 offset:52224
	ds_read_b128 v[192:195], v238 offset:53248
	ds_read_b128 v[196:199], v238 offset:54272
	ds_read_b128 v[200:203], v238 offset:55296
	ds_read_b128 v[204:207], v238 offset:56320
	global_load_lds_dwordx4 v[208:209], off
	s_add_i32 m0, s2, 0x2000
	s_add_u32 s2, s26, 0x80080
	v_lshl_add_u64 v[208:209], v[210:211], 0, s[0:1]
	s_addc_u32 s3, s27, 0
	s_add_i32 s26, s53, s34
	global_load_lds_dwordx4 v[208:209], off
	v_lshl_add_u64 v[208:209], s[2:3], 0, v[176:177]
	s_mov_b32 m0, s26
	s_nop 0
	global_load_lds_dwordx4 v[208:209], off
	v_lshl_add_u64 v[208:209], s[2:3], 0, v[186:187]
	s_add_i32 m0, s26, 0x2000
	s_nop 0
	global_load_lds_dwordx4 v[208:209], off
	v_lshl_add_u64 v[208:209], v[212:213], 0, s[0:1]
	s_mov_b32 m0, s42
	s_nop 0
	global_load_lds_dwordx4 v[208:209], off
	v_lshl_add_u64 v[208:209], v[214:215], 0, s[0:1]
	s_mov_b32 m0, s43
	s_nop 0
	global_load_lds_dwordx4 v[208:209], off
	s_waitcnt vmcnt(8)
	s_waitcnt lgkmcnt(0)
	s_setprio 1
	s_barrier
	v_mfma_f32_16x16x32_bf16 v[60:63], v[128:131], v[160:163], v[60:63]
	v_mfma_f32_16x16x32_bf16 v[56:59], v[136:139], v[160:163], v[56:59]
	v_mfma_f32_16x16x32_bf16 v[44:47], v[128:131], v[168:171], v[44:47]
	v_mfma_f32_16x16x32_bf16 v[40:43], v[136:139], v[168:171], v[40:43]
	v_mfma_f32_16x16x32_bf16 v[28:31], v[128:131], v[192:195], v[28:31]
	v_mfma_f32_16x16x32_bf16 v[24:27], v[136:139], v[192:195], v[24:27]
	v_mfma_f32_16x16x32_bf16 v[12:15], v[128:131], v[200:203], v[12:15]
	v_mfma_f32_16x16x32_bf16 v[8:11], v[136:139], v[200:203], v[8:11]
	s_setprio 0
	s_setprio 1
	v_mfma_f32_16x16x32_bf16 v[60:63], v[132:135], v[164:167], v[60:63]
	v_mfma_f32_16x16x32_bf16 v[56:59], v[140:143], v[164:167], v[56:59]
	v_mfma_f32_16x16x32_bf16 v[44:47], v[132:135], v[172:175], v[44:47]
	v_mfma_f32_16x16x32_bf16 v[40:43], v[140:143], v[172:175], v[40:43]
	v_mfma_f32_16x16x32_bf16 v[28:31], v[132:135], v[196:199], v[28:31]
	v_mfma_f32_16x16x32_bf16 v[24:27], v[140:143], v[196:199], v[24:27]
	v_mfma_f32_16x16x32_bf16 v[12:15], v[132:135], v[204:207], v[12:15]
	v_mfma_f32_16x16x32_bf16 v[8:11], v[140:143], v[204:207], v[8:11]
	s_setprio 0
	s_setprio 1
	v_mfma_f32_16x16x32_bf16 v[52:55], v[144:147], v[160:163], v[52:55]
	v_mfma_f32_16x16x32_bf16 v[48:51], v[152:155], v[160:163], v[48:51]
	v_mfma_f32_16x16x32_bf16 v[36:39], v[144:147], v[168:171], v[36:39]
	v_mfma_f32_16x16x32_bf16 v[32:35], v[152:155], v[168:171], v[32:35]
	v_mfma_f32_16x16x32_bf16 v[20:23], v[144:147], v[192:195], v[20:23]
	v_mfma_f32_16x16x32_bf16 v[16:19], v[152:155], v[192:195], v[16:19]
	v_mfma_f32_16x16x32_bf16 v[4:7], v[144:147], v[200:203], v[4:7]
	v_mfma_f32_16x16x32_bf16 v[0:3], v[152:155], v[200:203], v[0:3]
	s_setprio 0
	s_setprio 1
	v_mfma_f32_16x16x32_bf16 v[52:55], v[148:151], v[164:167], v[52:55]
	v_mfma_f32_16x16x32_bf16 v[48:51], v[156:159], v[164:167], v[48:51]
	v_mfma_f32_16x16x32_bf16 v[36:39], v[148:151], v[172:175], v[36:39]
	v_mfma_f32_16x16x32_bf16 v[32:35], v[156:159], v[172:175], v[32:35]
	v_mfma_f32_16x16x32_bf16 v[20:23], v[148:151], v[196:199], v[20:23]
	v_mfma_f32_16x16x32_bf16 v[16:19], v[156:159], v[196:199], v[16:19]
	v_mfma_f32_16x16x32_bf16 v[4:7], v[148:151], v[204:207], v[4:7]
	v_mfma_f32_16x16x32_bf16 v[0:3], v[156:159], v[204:207], v[0:3]
	s_barrier
	s_setprio 0
	s_add_i32 s51, s51, 2
	s_add_u32 s49, s49, 0x100
	s_addc_u32 s50, s50, 0
	s_cmp_gt_u32 s51, 29
	s_mov_b64 s[2:3], s[24:25]
	s_cbranch_scc0 .LBB0_50
	s_and_b64 vcc, exec, s[12:13]
	s_cbranch_vccz .LBB0_53
	s_barrier

.LBB0_291:
	s_add_u32 s8, s20, 0x100
	s_addc_u32 s9, s21, 0
	s_add_i32 s46, 0, 0x10000
	s_cmpk_eq_i32 s45, 0x54
	s_cselect_b32 s25, s17, s9
	s_cselect_b32 s24, s16, s8
	s_cselect_b32 s23, s19, s44
	s_cselect_b32 s22, s18, s43
	s_add_i32 s47, 0, 0x14000
	v_add_u32_e32 v146, s46, v215
	v_add_u32_e32 v162, s47, v215
	ds_read_b128 v[134:137], v146
	ds_read_b128 v[138:141], v146 offset:1024
	ds_read_b128 v[142:145], v146 offset:2048
	ds_read_b128 v[146:149], v146 offset:3072
	ds_read_b128 v[150:153], v162
	ds_read_b128 v[154:157], v162 offset:1024
	ds_read_b128 v[158:161], v162 offset:2048
	ds_read_b128 v[162:165], v162 offset:3072
	v_lshl_add_u64 v[174:175], s[20:21], 0, v[132:133]
	s_add_i32 m0, s29, 0xc000
	ds_read_b128 v[166:169], v217
	ds_read_b128 v[170:173], v217 offset:1024
	ds_read_b128 v[186:189], v217 offset:2048
	ds_read_b128 v[190:193], v217 offset:3072
	ds_read_b128 v[194:197], v217 offset:4096
	ds_read_b128 v[198:201], v217 offset:5120
	ds_read_b128 v[202:205], v217 offset:6144
	ds_read_b128 v[206:209], v217 offset:7168
	global_load_lds_dwordx4 v[174:175], off
	v_lshl_add_u64 v[174:175], s[20:21], 0, v[130:131]
	s_add_i32 m0, s29, 0xe000
	s_nop 0
	global_load_lds_dwordx4 v[174:175], off
	s_waitcnt vmcnt(8)
	s_waitcnt lgkmcnt(0)
	s_setprio 1
	s_barrier
	v_mfma_f32_16x16x32_bf16 v[124:127], v[134:137], v[166:169], v[124:127]
	v_mfma_f32_16x16x32_bf16 v[120:123], v[142:145], v[166:169], v[120:123]
	v_mfma_f32_16x16x32_bf16 v[108:111], v[134:137], v[186:189], v[108:111]
	v_mfma_f32_16x16x32_bf16 v[104:107], v[142:145], v[186:189], v[104:107]
	v_mfma_f32_16x16x32_bf16 v[92:95], v[134:137], v[194:197], v[92:95]
	v_mfma_f32_16x16x32_bf16 v[88:91], v[142:145], v[194:197], v[88:91]
	v_mfma_f32_16x16x32_bf16 v[76:79], v[134:137], v[202:205], v[76:79]
	v_mfma_f32_16x16x32_bf16 v[72:75], v[142:145], v[202:205], v[72:75]
	s_setprio 0
	s_setprio 1
	v_mfma_f32_16x16x32_bf16 v[124:127], v[138:141], v[170:173], v[124:127]
	v_mfma_f32_16x16x32_bf16 v[120:123], v[146:149], v[170:173], v[120:123]
	v_mfma_f32_16x16x32_bf16 v[108:111], v[138:141], v[190:193], v[108:111]
	v_mfma_f32_16x16x32_bf16 v[104:107], v[146:149], v[190:193], v[104:107]
	v_mfma_f32_16x16x32_bf16 v[92:95], v[138:141], v[198:201], v[92:95]
	v_mfma_f32_16x16x32_bf16 v[88:91], v[146:149], v[198:201], v[88:91]
	v_mfma_f32_16x16x32_bf16 v[76:79], v[138:141], v[206:209], v[76:79]
	v_mfma_f32_16x16x32_bf16 v[72:75], v[146:149], v[206:209], v[72:75]
	s_setprio 0
	s_setprio 1
	v_mfma_f32_16x16x32_bf16 v[116:119], v[150:153], v[166:169], v[116:119]
	v_mfma_f32_16x16x32_bf16 v[112:115], v[158:161], v[166:169], v[112:115]
	v_mfma_f32_16x16x32_bf16 v[100:103], v[150:153], v[186:189], v[100:103]
	v_mfma_f32_16x16x32_bf16 v[96:99], v[158:161], v[186:189], v[96:99]
	v_mfma_f32_16x16x32_bf16 v[84:87], v[150:153], v[194:197], v[84:87]
	v_mfma_f32_16x16x32_bf16 v[80:83], v[158:161], v[194:197], v[80:83]
	v_mfma_f32_16x16x32_bf16 v[68:71], v[150:153], v[202:205], v[68:71]
	v_mfma_f32_16x16x32_bf16 v[64:67], v[158:161], v[202:205], v[64:67]
	s_setprio 0
	s_setprio 1
	v_mfma_f32_16x16x32_bf16 v[116:119], v[154:157], v[170:173], v[116:119]
	v_mfma_f32_16x16x32_bf16 v[112:115], v[162:165], v[170:173], v[112:115]
	v_mfma_f32_16x16x32_bf16 v[100:103], v[154:157], v[190:193], v[100:103]
	v_mfma_f32_16x16x32_bf16 v[96:99], v[162:165], v[190:193], v[96:99]
	v_mfma_f32_16x16x32_bf16 v[84:87], v[154:157], v[198:201], v[84:87]
	v_mfma_f32_16x16x32_bf16 v[80:83], v[162:165], v[198:201], v[80:83]
	v_mfma_f32_16x16x32_bf16 v[68:71], v[154:157], v[206:209], v[68:71]
	v_mfma_f32_16x16x32_bf16 v[64:67], v[162:165], v[206:209], v[64:67]
	s_barrier
	s_setprio 0
	s_add_i32 s20, s46, s28
	v_lshl_add_u64 v[174:175], s[22:23], 0, v[176:177]
	s_mov_b32 m0, s20
	ds_read_b128 v[166:169], v217 offset:16384
	ds_read_b128 v[170:173], v217 offset:17408
	ds_read_b128 v[186:189], v217 offset:18432
	ds_read_b128 v[190:193], v217 offset:19456
	ds_read_b128 v[194:197], v217 offset:20480
	ds_read_b128 v[198:201], v217 offset:21504
	ds_read_b128 v[202:205], v217 offset:22528
	ds_read_b128 v[206:209], v217 offset:23552
	global_load_lds_dwordx4 v[174:175], off
	s_add_i32 m0, s20, 0x2000
	s_add_u32 s20, s22, 0x160000
	v_lshl_add_u64 v[210:211], s[22:23], 0, v[128:129]
	s_addc_u32 s21, s23, 0
	s_add_i32 s46, s47, s28
	global_load_lds_dwordx4 v[210:211], off
	v_lshl_add_u64 v[212:213], s[20:21], 0, v[176:177]
	s_mov_b32 m0, s46
	v_lshl_add_u64 v[218:219], s[24:25], 0, v[128:129]
	global_load_lds_dwordx4 v[212:213], off
	v_lshl_add_u64 v[212:213], s[20:21], 0, v[128:129]
	s_add_i32 m0, s46, 0x2000
	s_nop 0
	global_load_lds_dwordx4 v[212:213], off
	v_lshl_add_u64 v[212:213], s[24:25], 0, v[176:177]
	s_mov_b32 m0, s29
	s_nop 0
	global_load_lds_dwordx4 v[212:213], off
	s_mov_b32 m0, s30
	s_nop 0
	global_load_lds_dwordx4 v[218:219], off
	s_waitcnt vmcnt(8)
	s_waitcnt lgkmcnt(0)
	s_setprio 1
	s_barrier
	v_mfma_f32_16x16x32_bf16 v[60:63], v[134:137], v[166:169], v[60:63]
	v_mfma_f32_16x16x32_bf16 v[56:59], v[142:145], v[166:169], v[56:59]
	v_mfma_f32_16x16x32_bf16 v[44:47], v[134:137], v[186:189], v[44:47]
	v_mfma_f32_16x16x32_bf16 v[40:43], v[142:145], v[186:189], v[40:43]
	v_mfma_f32_16x16x32_bf16 v[28:31], v[134:137], v[194:197], v[28:31]
	v_mfma_f32_16x16x32_bf16 v[24:27], v[142:145], v[194:197], v[24:27]
	v_mfma_f32_16x16x32_bf16 v[12:15], v[134:137], v[202:205], v[12:15]
	v_mfma_f32_16x16x32_bf16 v[8:11], v[142:145], v[202:205], v[8:11]
	s_setprio 0
	s_setprio 1
	v_mfma_f32_16x16x32_bf16 v[60:63], v[138:141], v[170:173], v[60:63]
	v_mfma_f32_16x16x32_bf16 v[56:59], v[146:149], v[170:173], v[56:59]
	v_mfma_f32_16x16x32_bf16 v[44:47], v[138:141], v[190:193], v[44:47]
	v_mfma_f32_16x16x32_bf16 v[40:43], v[146:149], v[190:193], v[40:43]
	v_mfma_f32_16x16x32_bf16 v[28:31], v[138:141], v[198:201], v[28:31]
	v_mfma_f32_16x16x32_bf16 v[24:27], v[146:149], v[198:201], v[24:27]
	v_mfma_f32_16x16x32_bf16 v[12:15], v[138:141], v[206:209], v[12:15]
	v_mfma_f32_16x16x32_bf16 v[8:11], v[146:149], v[206:209], v[8:11]
	s_setprio 0
	s_setprio 1
	v_mfma_f32_16x16x32_bf16 v[52:55], v[150:153], v[166:169], v[52:55]
	v_mfma_f32_16x16x32_bf16 v[48:51], v[158:161], v[166:169], v[48:51]
	v_mfma_f32_16x16x32_bf16 v[36:39], v[150:153], v[186:189], v[36:39]
	v_mfma_f32_16x16x32_bf16 v[32:35], v[158:161], v[186:189], v[32:35]
	v_mfma_f32_16x16x32_bf16 v[20:23], v[150:153], v[194:197], v[20:23]
	v_mfma_f32_16x16x32_bf16 v[16:19], v[158:161], v[194:197], v[16:19]
	v_mfma_f32_16x16x32_bf16 v[4:7], v[150:153], v[202:205], v[4:7]
	v_mfma_f32_16x16x32_bf16 v[0:3], v[158:161], v[202:205], v[0:3]
	s_setprio 0
	s_setprio 1
	v_mfma_f32_16x16x32_bf16 v[52:55], v[154:157], v[170:173], v[52:55]
	v_mfma_f32_16x16x32_bf16 v[48:51], v[162:165], v[170:173], v[48:51]
	v_mfma_f32_16x16x32_bf16 v[36:39], v[154:157], v[190:193], v[36:39]
	v_mfma_f32_16x16x32_bf16 v[32:35], v[162:165], v[190:193], v[32:35]
	v_mfma_f32_16x16x32_bf16 v[20:23], v[154:157], v[198:201], v[20:23]
	v_mfma_f32_16x16x32_bf16 v[16:19], v[162:165], v[198:201], v[16:19]
	v_mfma_f32_16x16x32_bf16 v[4:7], v[154:157], v[206:209], v[4:7]
	v_mfma_f32_16x16x32_bf16 v[0:3], v[162:165], v[206:209], v[0:3]
	s_barrier
	s_setprio 0
	s_add_i32 s46, 0, 0x18000
	s_add_i32 s47, 0, 0x1c000
	v_add_u32_e32 v146, s46, v215
	v_add_u32_e32 v162, s47, v215
	ds_read_b128 v[134:137], v146
	ds_read_b128 v[138:141], v146 offset:1024
	ds_read_b128 v[142:145], v146 offset:2048
	ds_read_b128 v[146:149], v146 offset:3072
	ds_read_b128 v[150:153], v162
	ds_read_b128 v[154:157], v162 offset:1024
	ds_read_b128 v[158:161], v162 offset:2048
	ds_read_b128 v[162:165], v162 offset:3072
	s_add_u32 s20, s24, 0x160000
	s_addc_u32 s21, s25, 0
	s_mov_b32 m0, s31
	v_lshl_add_u64 v[228:229], s[20:21], 0, v[176:177]
	ds_read_b128 v[166:169], v217 offset:32768
	ds_read_b128 v[170:173], v217 offset:33792
	ds_read_b128 v[186:189], v217 offset:34816
	ds_read_b128 v[190:193], v217 offset:35840
	ds_read_b128 v[194:197], v217 offset:36864
	ds_read_b128 v[198:201], v217 offset:37888
	ds_read_b128 v[202:205], v217 offset:38912
	ds_read_b128 v[206:209], v217 offset:39936
	global_load_lds_dwordx4 v[228:229], off
	v_lshl_add_u64 v[228:229], s[20:21], 0, v[128:129]
	s_mov_b32 m0, s34
	s_nop 0
	global_load_lds_dwordx4 v[228:229], off
	s_waitcnt vmcnt(8)
	s_waitcnt lgkmcnt(0)
	s_setprio 1
	s_barrier
	v_mfma_f32_16x16x32_bf16 v[124:127], v[134:137], v[166:169], v[124:127]
	v_mfma_f32_16x16x32_bf16 v[120:123], v[142:145], v[166:169], v[120:123]
	v_mfma_f32_16x16x32_bf16 v[108:111], v[134:137], v[186:189], v[108:111]
	v_mfma_f32_16x16x32_bf16 v[104:107], v[142:145], v[186:189], v[104:107]
	v_mfma_f32_16x16x32_bf16 v[92:95], v[134:137], v[194:197], v[92:95]
	v_mfma_f32_16x16x32_bf16 v[88:91], v[142:145], v[194:197], v[88:91]
	v_mfma_f32_16x16x32_bf16 v[76:79], v[134:137], v[202:205], v[76:79]
	v_mfma_f32_16x16x32_bf16 v[72:75], v[142:145], v[202:205], v[72:75]
	s_setprio 0
	s_setprio 1
	v_mfma_f32_16x16x32_bf16 v[124:127], v[138:141], v[170:173], v[124:127]
	v_mfma_f32_16x16x32_bf16 v[120:123], v[146:149], v[170:173], v[120:123]
	v_mfma_f32_16x16x32_bf16 v[108:111], v[138:141], v[190:193], v[108:111]
	v_mfma_f32_16x16x32_bf16 v[104:107], v[146:149], v[190:193], v[104:107]
	v_mfma_f32_16x16x32_bf16 v[92:95], v[138:141], v[198:201], v[92:95]
	v_mfma_f32_16x16x32_bf16 v[88:91], v[146:149], v[198:201], v[88:91]
	v_mfma_f32_16x16x32_bf16 v[76:79], v[138:141], v[206:209], v[76:79]
	v_mfma_f32_16x16x32_bf16 v[72:75], v[146:149], v[206:209], v[72:75]
	s_setprio 0
	s_setprio 1
	v_mfma_f32_16x16x32_bf16 v[116:119], v[150:153], v[166:169], v[116:119]
	v_mfma_f32_16x16x32_bf16 v[112:115], v[158:161], v[166:169], v[112:115]
	v_mfma_f32_16x16x32_bf16 v[100:103], v[150:153], v[186:189], v[100:103]
	v_mfma_f32_16x16x32_bf16 v[96:99], v[158:161], v[186:189], v[96:99]
	v_mfma_f32_16x16x32_bf16 v[84:87], v[150:153], v[194:197], v[84:87]
	v_mfma_f32_16x16x32_bf16 v[80:83], v[158:161], v[194:197], v[80:83]
	v_mfma_f32_16x16x32_bf16 v[68:71], v[150:153], v[202:205], v[68:71]
	v_mfma_f32_16x16x32_bf16 v[64:67], v[158:161], v[202:205], v[64:67]
	s_setprio 0
	s_setprio 1
	v_mfma_f32_16x16x32_bf16 v[116:119], v[154:157], v[170:173], v[116:119]
	v_mfma_f32_16x16x32_bf16 v[112:115], v[162:165], v[170:173], v[112:115]
	v_mfma_f32_16x16x32_bf16 v[100:103], v[154:157], v[190:193], v[100:103]
	v_mfma_f32_16x16x32_bf16 v[96:99], v[162:165], v[190:193], v[96:99]
	v_mfma_f32_16x16x32_bf16 v[84:87], v[154:157], v[198:201], v[84:87]
	v_mfma_f32_16x16x32_bf16 v[80:83], v[162:165], v[198:201], v[80:83]
	v_mfma_f32_16x16x32_bf16 v[68:71], v[154:157], v[206:209], v[68:71]
	v_mfma_f32_16x16x32_bf16 v[64:67], v[162:165], v[206:209], v[64:67]
	s_barrier
	s_setprio 0
	s_add_i32 s20, s46, s28
	v_lshl_add_u64 v[174:175], v[174:175], 0, s[0:1]
	s_mov_b32 m0, s20
	ds_read_b128 v[166:169], v217 offset:49152
	ds_read_b128 v[170:173], v217 offset:50176
	ds_read_b128 v[186:189], v217 offset:51200
	ds_read_b128 v[190:193], v217 offset:52224
	ds_read_b128 v[194:197], v217 offset:53248
	ds_read_b128 v[198:201], v217 offset:54272
	ds_read_b128 v[202:205], v217 offset:55296
	ds_read_b128 v[206:209], v217 offset:56320
	global_load_lds_dwordx4 v[174:175], off
	s_add_i32 m0, s20, 0x2000
	s_add_u32 s20, s22, 0x160080
	v_lshl_add_u64 v[174:175], v[210:211], 0, s[0:1]
	s_addc_u32 s21, s23, 0
	s_add_i32 s22, s47, s28
	global_load_lds_dwordx4 v[174:175], off
	v_lshl_add_u64 v[174:175], s[20:21], 0, v[176:177]
	s_mov_b32 m0, s22
	s_nop 0
	global_load_lds_dwordx4 v[174:175], off
	v_lshl_add_u64 v[174:175], s[20:21], 0, v[128:129]
	s_add_i32 m0, s22, 0x2000
	s_nop 0
	global_load_lds_dwordx4 v[174:175], off
	v_lshl_add_u64 v[174:175], v[212:213], 0, s[0:1]
	s_mov_b32 m0, s36
	s_nop 0
	global_load_lds_dwordx4 v[174:175], off
	v_lshl_add_u64 v[174:175], v[218:219], 0, s[0:1]
	s_mov_b32 m0, s37
	s_nop 0
	global_load_lds_dwordx4 v[174:175], off
	s_waitcnt vmcnt(8)
	s_waitcnt lgkmcnt(0)
	s_setprio 1
	s_barrier
	v_mfma_f32_16x16x32_bf16 v[60:63], v[134:137], v[166:169], v[60:63]
	v_mfma_f32_16x16x32_bf16 v[56:59], v[142:145], v[166:169], v[56:59]
	v_mfma_f32_16x16x32_bf16 v[44:47], v[134:137], v[186:189], v[44:47]
	v_mfma_f32_16x16x32_bf16 v[40:43], v[142:145], v[186:189], v[40:43]
	v_mfma_f32_16x16x32_bf16 v[28:31], v[134:137], v[194:197], v[28:31]
	v_mfma_f32_16x16x32_bf16 v[24:27], v[142:145], v[194:197], v[24:27]
	v_mfma_f32_16x16x32_bf16 v[12:15], v[134:137], v[202:205], v[12:15]
	v_mfma_f32_16x16x32_bf16 v[8:11], v[142:145], v[202:205], v[8:11]
	s_setprio 0
	s_setprio 1
	v_mfma_f32_16x16x32_bf16 v[60:63], v[138:141], v[170:173], v[60:63]
	v_mfma_f32_16x16x32_bf16 v[56:59], v[146:149], v[170:173], v[56:59]
	v_mfma_f32_16x16x32_bf16 v[44:47], v[138:141], v[190:193], v[44:47]
	v_mfma_f32_16x16x32_bf16 v[40:43], v[146:149], v[190:193], v[40:43]
	v_mfma_f32_16x16x32_bf16 v[28:31], v[138:141], v[198:201], v[28:31]
	v_mfma_f32_16x16x32_bf16 v[24:27], v[146:149], v[198:201], v[24:27]
	v_mfma_f32_16x16x32_bf16 v[12:15], v[138:141], v[206:209], v[12:15]
	v_mfma_f32_16x16x32_bf16 v[8:11], v[146:149], v[206:209], v[8:11]
	s_setprio 0
	s_setprio 1
	v_mfma_f32_16x16x32_bf16 v[52:55], v[150:153], v[166:169], v[52:55]
	v_mfma_f32_16x16x32_bf16 v[48:51], v[158:161], v[166:169], v[48:51]
	v_mfma_f32_16x16x32_bf16 v[36:39], v[150:153], v[186:189], v[36:39]
	v_mfma_f32_16x16x32_bf16 v[32:35], v[158:161], v[186:189], v[32:35]
	v_mfma_f32_16x16x32_bf16 v[20:23], v[150:153], v[194:197], v[20:23]
	v_mfma_f32_16x16x32_bf16 v[16:19], v[158:161], v[194:197], v[16:19]
	v_mfma_f32_16x16x32_bf16 v[4:7], v[150:153], v[202:205], v[4:7]
	v_mfma_f32_16x16x32_bf16 v[0:3], v[158:161], v[202:205], v[0:3]
	s_setprio 0
	s_setprio 1
	v_mfma_f32_16x16x32_bf16 v[52:55], v[154:157], v[170:173], v[52:55]
	v_mfma_f32_16x16x32_bf16 v[48:51], v[162:165], v[170:173], v[48:51]
	v_mfma_f32_16x16x32_bf16 v[36:39], v[154:157], v[190:193], v[36:39]
	v_mfma_f32_16x16x32_bf16 v[32:35], v[162:165], v[190:193], v[32:35]
	v_mfma_f32_16x16x32_bf16 v[20:23], v[154:157], v[198:201], v[20:23]
	v_mfma_f32_16x16x32_bf16 v[16:19], v[162:165], v[198:201], v[16:19]
	v_mfma_f32_16x16x32_bf16 v[4:7], v[154:157], v[206:209], v[4:7]
	v_mfma_f32_16x16x32_bf16 v[0:3], v[162:165], v[206:209], v[0:3]
	s_barrier
	s_setprio 0
	s_add_i32 s45, s45, 2
	s_add_u32 s43, s43, 0x100
	s_addc_u32 s44, s44, 0
	s_cmpk_gt_u32 s45, 0x55
	s_mov_b64 s[20:21], s[8:9]
	s_cbranch_scc0 .LBB0_291
	s_and_b64 vcc, exec, s[14:15]
	s_cbranch_vccz .LBB0_294
	s_barrier

.LBB0_474:
	s_add_u32 s20, s18, 0xfff80080
	s_addc_u32 s21, s19, -1
	s_add_i32 s45, 0, 0x10000
	s_cmp_eq_u32 s44, 28
	s_cselect_b32 s23, s13, s21
	s_cselect_b32 s22, s40, s20
	v_add_u32_e32 v139, s45, v137
	s_cselect_b32 s21, s11, s43
	s_cselect_b32 s20, s41, s42
	s_add_i32 s48, 0, 0x14000
	ds_read_b128 v[140:143], v139
	ds_read_b128 v[144:147], v139 offset:1024
	ds_read_b128 v[148:151], v139 offset:2048
	ds_read_b128 v[152:155], v139 offset:3072
	v_add_u32_e32 v139, s48, v137
	ds_read_b128 v[156:159], v139
	ds_read_b128 v[160:163], v139 offset:1024
	ds_read_b128 v[164:167], v139 offset:2048
	ds_read_b128 v[168:171], v139 offset:3072
	v_lshl_add_u64 v[214:215], s[18:19], 0, v[134:135]
	s_add_i32 m0, s29, 0xc000
	ds_read_b128 v[172:175], v138
	ds_read_b128 v[186:189], v138 offset:1024
	ds_read_b128 v[190:193], v138 offset:2048
	ds_read_b128 v[194:197], v138 offset:3072
	ds_read_b128 v[198:201], v138 offset:4096
	ds_read_b128 v[202:205], v138 offset:5120
	ds_read_b128 v[206:209], v138 offset:6144
	ds_read_b128 v[210:213], v138 offset:7168
	global_load_lds_dwordx4 v[214:215], off
	v_lshl_add_u64 v[214:215], s[18:19], 0, v[132:133]
	s_add_i32 m0, s29, 0xe000
	s_nop 0
	global_load_lds_dwordx4 v[214:215], off
	s_waitcnt vmcnt(8)
	s_waitcnt lgkmcnt(0)
	s_setprio 1
	s_barrier
	v_mfma_f32_16x16x32_bf16 v[124:127], v[140:143], v[172:175], v[124:127]
	v_mfma_f32_16x16x32_bf16 v[120:123], v[148:151], v[172:175], v[120:123]
	v_mfma_f32_16x16x32_bf16 v[116:119], v[140:143], v[190:193], v[116:119]
	v_mfma_f32_16x16x32_bf16 v[108:111], v[148:151], v[190:193], v[108:111]
	v_mfma_f32_16x16x32_bf16 v[100:103], v[140:143], v[198:201], v[100:103]
	v_mfma_f32_16x16x32_bf16 v[92:95], v[148:151], v[198:201], v[92:95]
	v_mfma_f32_16x16x32_bf16 v[84:87], v[140:143], v[206:209], v[84:87]
	v_mfma_f32_16x16x32_bf16 v[76:79], v[148:151], v[206:209], v[76:79]
	s_setprio 0
	s_setprio 1
	v_mfma_f32_16x16x32_bf16 v[124:127], v[144:147], v[186:189], v[124:127]
	v_mfma_f32_16x16x32_bf16 v[120:123], v[152:155], v[186:189], v[120:123]
	v_mfma_f32_16x16x32_bf16 v[116:119], v[144:147], v[194:197], v[116:119]
	v_mfma_f32_16x16x32_bf16 v[108:111], v[152:155], v[194:197], v[108:111]
	v_mfma_f32_16x16x32_bf16 v[100:103], v[144:147], v[202:205], v[100:103]
	v_mfma_f32_16x16x32_bf16 v[92:95], v[152:155], v[202:205], v[92:95]
	v_mfma_f32_16x16x32_bf16 v[84:87], v[144:147], v[210:213], v[84:87]
	v_mfma_f32_16x16x32_bf16 v[76:79], v[152:155], v[210:213], v[76:79]
	s_setprio 0
	s_setprio 1
	v_mfma_f32_16x16x32_bf16 v[112:115], v[156:159], v[172:175], v[112:115]
	v_mfma_f32_16x16x32_bf16 v[104:107], v[164:167], v[172:175], v[104:107]
	v_mfma_f32_16x16x32_bf16 v[96:99], v[156:159], v[190:193], v[96:99]
	v_mfma_f32_16x16x32_bf16 v[88:91], v[164:167], v[190:193], v[88:91]
	v_mfma_f32_16x16x32_bf16 v[80:83], v[156:159], v[198:201], v[80:83]
	v_mfma_f32_16x16x32_bf16 v[72:75], v[164:167], v[198:201], v[72:75]
	v_mfma_f32_16x16x32_bf16 v[68:71], v[156:159], v[206:209], v[68:71]
	v_mfma_f32_16x16x32_bf16 v[64:67], v[164:167], v[206:209], v[64:67]
	s_setprio 0
	s_setprio 1
	v_mfma_f32_16x16x32_bf16 v[112:115], v[160:163], v[186:189], v[112:115]
	v_mfma_f32_16x16x32_bf16 v[104:107], v[168:171], v[186:189], v[104:107]
	v_mfma_f32_16x16x32_bf16 v[96:99], v[160:163], v[194:197], v[96:99]
	v_mfma_f32_16x16x32_bf16 v[88:91], v[168:171], v[194:197], v[88:91]
	v_mfma_f32_16x16x32_bf16 v[80:83], v[160:163], v[202:205], v[80:83]
	v_mfma_f32_16x16x32_bf16 v[72:75], v[168:171], v[202:205], v[72:75]
	v_mfma_f32_16x16x32_bf16 v[68:71], v[160:163], v[210:213], v[68:71]
	v_mfma_f32_16x16x32_bf16 v[64:67], v[168:171], v[210:213], v[64:67]
	s_barrier
	s_setprio 0
	s_add_i32 s45, s45, s28
	v_lshl_add_u64 v[214:215], s[20:21], 0, v[130:131]
	s_mov_b32 m0, s45
	ds_read_b128 v[172:175], v138 offset:16384
	ds_read_b128 v[186:189], v138 offset:17408
	ds_read_b128 v[190:193], v138 offset:18432
	ds_read_b128 v[194:197], v138 offset:19456
	ds_read_b128 v[198:201], v138 offset:20480
	ds_read_b128 v[202:205], v138 offset:21504
	ds_read_b128 v[206:209], v138 offset:22528
	ds_read_b128 v[210:213], v138 offset:23552
	global_load_lds_dwordx4 v[214:215], off
	s_add_i32 m0, s45, 0x2000
	s_add_u32 s46, s20, 0x80000
	v_lshl_add_u64 v[216:217], s[20:21], 0, v[128:129]
	s_addc_u32 s47, s21, 0
	s_add_i32 s45, s48, s28
	global_load_lds_dwordx4 v[216:217], off
	v_lshl_add_u64 v[218:219], s[46:47], 0, v[130:131]
	s_mov_b32 m0, s45
	v_lshl_add_u64 v[228:229], s[22:23], 0, v[128:129]
	global_load_lds_dwordx4 v[218:219], off
	v_lshl_add_u64 v[218:219], s[46:47], 0, v[128:129]
	s_add_i32 m0, s45, 0x2000
	s_nop 0
	global_load_lds_dwordx4 v[218:219], off
	v_lshl_add_u64 v[218:219], s[22:23], 0, v[130:131]
	s_mov_b32 m0, s29
	s_nop 0
	global_load_lds_dwordx4 v[218:219], off
	s_mov_b32 m0, s30
	s_nop 0
	global_load_lds_dwordx4 v[228:229], off
	s_waitcnt vmcnt(8)
	s_waitcnt lgkmcnt(0)
	s_setprio 1
	s_barrier
	v_mfma_f32_16x16x32_bf16 v[60:63], v[140:143], v[172:175], v[60:63]
	v_mfma_f32_16x16x32_bf16 v[56:59], v[148:151], v[172:175], v[56:59]
	v_mfma_f32_16x16x32_bf16 v[52:55], v[140:143], v[190:193], v[52:55]
	v_mfma_f32_16x16x32_bf16 v[44:47], v[148:151], v[190:193], v[44:47]
	v_mfma_f32_16x16x32_bf16 v[36:39], v[140:143], v[198:201], v[36:39]
	v_mfma_f32_16x16x32_bf16 v[28:31], v[148:151], v[198:201], v[28:31]
	v_mfma_f32_16x16x32_bf16 v[20:23], v[140:143], v[206:209], v[20:23]
	v_mfma_f32_16x16x32_bf16 v[12:15], v[148:151], v[206:209], v[12:15]
	s_setprio 0
	s_setprio 1
	v_mfma_f32_16x16x32_bf16 v[60:63], v[144:147], v[186:189], v[60:63]
	v_mfma_f32_16x16x32_bf16 v[56:59], v[152:155], v[186:189], v[56:59]
	v_mfma_f32_16x16x32_bf16 v[52:55], v[144:147], v[194:197], v[52:55]
	v_mfma_f32_16x16x32_bf16 v[44:47], v[152:155], v[194:197], v[44:47]
	v_mfma_f32_16x16x32_bf16 v[36:39], v[144:147], v[202:205], v[36:39]
	v_mfma_f32_16x16x32_bf16 v[28:31], v[152:155], v[202:205], v[28:31]
	v_mfma_f32_16x16x32_bf16 v[20:23], v[144:147], v[210:213], v[20:23]
	v_mfma_f32_16x16x32_bf16 v[12:15], v[152:155], v[210:213], v[12:15]
	s_setprio 0
	s_setprio 1
	v_mfma_f32_16x16x32_bf16 v[48:51], v[156:159], v[172:175], v[48:51]
	v_mfma_f32_16x16x32_bf16 v[40:43], v[164:167], v[172:175], v[40:43]
	v_mfma_f32_16x16x32_bf16 v[32:35], v[156:159], v[190:193], v[32:35]
	v_mfma_f32_16x16x32_bf16 v[24:27], v[164:167], v[190:193], v[24:27]
	v_mfma_f32_16x16x32_bf16 v[16:19], v[156:159], v[198:201], v[16:19]
	v_mfma_f32_16x16x32_bf16 v[8:11], v[164:167], v[198:201], v[8:11]
	v_mfma_f32_16x16x32_bf16 v[4:7], v[156:159], v[206:209], v[4:7]
	v_mfma_f32_16x16x32_bf16 v[0:3], v[164:167], v[206:209], v[0:3]
	s_setprio 0
	s_setprio 1
	v_mfma_f32_16x16x32_bf16 v[48:51], v[160:163], v[186:189], v[48:51]
	v_mfma_f32_16x16x32_bf16 v[40:43], v[168:171], v[186:189], v[40:43]
	v_mfma_f32_16x16x32_bf16 v[32:35], v[160:163], v[194:197], v[32:35]
	v_mfma_f32_16x16x32_bf16 v[24:27], v[168:171], v[194:197], v[24:27]
	v_mfma_f32_16x16x32_bf16 v[16:19], v[160:163], v[202:205], v[16:19]
	v_mfma_f32_16x16x32_bf16 v[8:11], v[168:171], v[202:205], v[8:11]
	v_mfma_f32_16x16x32_bf16 v[4:7], v[160:163], v[210:213], v[4:7]
	v_mfma_f32_16x16x32_bf16 v[0:3], v[168:171], v[210:213], v[0:3]
	s_barrier
	s_setprio 0
	s_add_i32 s45, 0, 0x18000
	v_add_u32_e32 v139, s45, v137
	s_add_i32 s46, 0, 0x1c000
	ds_read_b128 v[140:143], v139
	ds_read_b128 v[144:147], v139 offset:1024
	ds_read_b128 v[148:151], v139 offset:2048
	ds_read_b128 v[152:155], v139 offset:3072
	v_add_u32_e32 v139, s46, v137
	ds_read_b128 v[156:159], v139
	ds_read_b128 v[160:163], v139 offset:1024
	ds_read_b128 v[164:167], v139 offset:2048
	ds_read_b128 v[168:171], v139 offset:3072
	s_add_u32 s22, s22, 0x80000
	s_addc_u32 s23, s23, 0
	s_mov_b32 m0, s31
	v_lshl_add_u64 v[230:231], s[22:23], 0, v[130:131]
	ds_read_b128 v[172:175], v138 offset:32768
	ds_read_b128 v[186:189], v138 offset:33792
	ds_read_b128 v[190:193], v138 offset:34816
	ds_read_b128 v[194:197], v138 offset:35840
	ds_read_b128 v[198:201], v138 offset:36864
	ds_read_b128 v[202:205], v138 offset:37888
	ds_read_b128 v[206:209], v138 offset:38912
	ds_read_b128 v[210:213], v138 offset:39936
	global_load_lds_dwordx4 v[230:231], off
	v_lshl_add_u64 v[230:231], s[22:23], 0, v[128:129]
	s_mov_b32 m0, s34
	s_nop 0
	global_load_lds_dwordx4 v[230:231], off
	s_waitcnt vmcnt(8)
	s_waitcnt lgkmcnt(0)
	s_setprio 1
	s_barrier
	v_mfma_f32_16x16x32_bf16 v[124:127], v[140:143], v[172:175], v[124:127]
	v_mfma_f32_16x16x32_bf16 v[120:123], v[148:151], v[172:175], v[120:123]
	v_mfma_f32_16x16x32_bf16 v[116:119], v[140:143], v[190:193], v[116:119]
	v_mfma_f32_16x16x32_bf16 v[108:111], v[148:151], v[190:193], v[108:111]
	v_mfma_f32_16x16x32_bf16 v[100:103], v[140:143], v[198:201], v[100:103]
	v_mfma_f32_16x16x32_bf16 v[92:95], v[148:151], v[198:201], v[92:95]
	v_mfma_f32_16x16x32_bf16 v[84:87], v[140:143], v[206:209], v[84:87]
	v_mfma_f32_16x16x32_bf16 v[76:79], v[148:151], v[206:209], v[76:79]
	s_setprio 0
	s_setprio 1
	v_mfma_f32_16x16x32_bf16 v[124:127], v[144:147], v[186:189], v[124:127]
	v_mfma_f32_16x16x32_bf16 v[120:123], v[152:155], v[186:189], v[120:123]
	v_mfma_f32_16x16x32_bf16 v[116:119], v[144:147], v[194:197], v[116:119]
	v_mfma_f32_16x16x32_bf16 v[108:111], v[152:155], v[194:197], v[108:111]
	v_mfma_f32_16x16x32_bf16 v[100:103], v[144:147], v[202:205], v[100:103]
	v_mfma_f32_16x16x32_bf16 v[92:95], v[152:155], v[202:205], v[92:95]
	v_mfma_f32_16x16x32_bf16 v[84:87], v[144:147], v[210:213], v[84:87]
	v_mfma_f32_16x16x32_bf16 v[76:79], v[152:155], v[210:213], v[76:79]
	s_setprio 0
	s_setprio 1
	v_mfma_f32_16x16x32_bf16 v[112:115], v[156:159], v[172:175], v[112:115]
	v_mfma_f32_16x16x32_bf16 v[104:107], v[164:167], v[172:175], v[104:107]
	v_mfma_f32_16x16x32_bf16 v[96:99], v[156:159], v[190:193], v[96:99]
	v_mfma_f32_16x16x32_bf16 v[88:91], v[164:167], v[190:193], v[88:91]
	v_mfma_f32_16x16x32_bf16 v[80:83], v[156:159], v[198:201], v[80:83]
	v_mfma_f32_16x16x32_bf16 v[72:75], v[164:167], v[198:201], v[72:75]
	v_mfma_f32_16x16x32_bf16 v[68:71], v[156:159], v[206:209], v[68:71]
	v_mfma_f32_16x16x32_bf16 v[64:67], v[164:167], v[206:209], v[64:67]
	s_setprio 0
	s_setprio 1
	v_mfma_f32_16x16x32_bf16 v[112:115], v[160:163], v[186:189], v[112:115]
	v_mfma_f32_16x16x32_bf16 v[104:107], v[168:171], v[186:189], v[104:107]
	v_mfma_f32_16x16x32_bf16 v[96:99], v[160:163], v[194:197], v[96:99]
	v_mfma_f32_16x16x32_bf16 v[88:91], v[168:171], v[194:197], v[88:91]
	v_mfma_f32_16x16x32_bf16 v[80:83], v[160:163], v[202:205], v[80:83]
	v_mfma_f32_16x16x32_bf16 v[72:75], v[168:171], v[202:205], v[72:75]
	v_mfma_f32_16x16x32_bf16 v[68:71], v[160:163], v[210:213], v[68:71]
	v_mfma_f32_16x16x32_bf16 v[64:67], v[168:171], v[210:213], v[64:67]
	s_barrier
	s_setprio 0
	s_add_i32 s22, s45, s28
	v_lshl_add_u64 v[214:215], v[214:215], 0, s[0:1]
	s_mov_b32 m0, s22
	ds_read_b128 v[172:175], v138 offset:49152
	ds_read_b128 v[186:189], v138 offset:50176
	ds_read_b128 v[190:193], v138 offset:51200
	ds_read_b128 v[194:197], v138 offset:52224
	ds_read_b128 v[198:201], v138 offset:53248
	ds_read_b128 v[202:205], v138 offset:54272
	ds_read_b128 v[206:209], v138 offset:55296
	ds_read_b128 v[210:213], v138 offset:56320
	global_load_lds_dwordx4 v[214:215], off
	s_add_i32 m0, s22, 0x2000
	s_add_u32 s20, s20, 0x80080
	v_lshl_add_u64 v[214:215], v[216:217], 0, s[0:1]
	s_addc_u32 s21, s21, 0
	s_add_i32 s22, s46, s28
	global_load_lds_dwordx4 v[214:215], off
	v_lshl_add_u64 v[214:215], s[20:21], 0, v[130:131]
	s_mov_b32 m0, s22
	s_nop 0
	global_load_lds_dwordx4 v[214:215], off
	v_lshl_add_u64 v[214:215], s[20:21], 0, v[128:129]
	s_add_i32 m0, s22, 0x2000
	s_nop 0
	global_load_lds_dwordx4 v[214:215], off
	v_lshl_add_u64 v[214:215], v[218:219], 0, s[0:1]
	s_mov_b32 m0, s35
	s_nop 0
	global_load_lds_dwordx4 v[214:215], off
	v_lshl_add_u64 v[214:215], v[228:229], 0, s[0:1]
	s_mov_b32 m0, s36
	s_nop 0
	global_load_lds_dwordx4 v[214:215], off
	s_waitcnt vmcnt(8)
	s_waitcnt lgkmcnt(0)
	s_setprio 1
	s_barrier
	v_mfma_f32_16x16x32_bf16 v[60:63], v[140:143], v[172:175], v[60:63]
	v_mfma_f32_16x16x32_bf16 v[56:59], v[148:151], v[172:175], v[56:59]
	v_mfma_f32_16x16x32_bf16 v[52:55], v[140:143], v[190:193], v[52:55]
	v_mfma_f32_16x16x32_bf16 v[44:47], v[148:151], v[190:193], v[44:47]
	v_mfma_f32_16x16x32_bf16 v[36:39], v[140:143], v[198:201], v[36:39]
	v_mfma_f32_16x16x32_bf16 v[28:31], v[148:151], v[198:201], v[28:31]
	v_mfma_f32_16x16x32_bf16 v[20:23], v[140:143], v[206:209], v[20:23]
	v_mfma_f32_16x16x32_bf16 v[12:15], v[148:151], v[206:209], v[12:15]
	s_setprio 0
	s_setprio 1
	v_mfma_f32_16x16x32_bf16 v[60:63], v[144:147], v[186:189], v[60:63]
	v_mfma_f32_16x16x32_bf16 v[56:59], v[152:155], v[186:189], v[56:59]
	v_mfma_f32_16x16x32_bf16 v[52:55], v[144:147], v[194:197], v[52:55]
	v_mfma_f32_16x16x32_bf16 v[44:47], v[152:155], v[194:197], v[44:47]
	v_mfma_f32_16x16x32_bf16 v[36:39], v[144:147], v[202:205], v[36:39]
	v_mfma_f32_16x16x32_bf16 v[28:31], v[152:155], v[202:205], v[28:31]
	v_mfma_f32_16x16x32_bf16 v[20:23], v[144:147], v[210:213], v[20:23]
	v_mfma_f32_16x16x32_bf16 v[12:15], v[152:155], v[210:213], v[12:15]
	s_setprio 0
	s_setprio 1
	v_mfma_f32_16x16x32_bf16 v[48:51], v[156:159], v[172:175], v[48:51]
	v_mfma_f32_16x16x32_bf16 v[40:43], v[164:167], v[172:175], v[40:43]
	v_mfma_f32_16x16x32_bf16 v[32:35], v[156:159], v[190:193], v[32:35]
	v_mfma_f32_16x16x32_bf16 v[24:27], v[164:167], v[190:193], v[24:27]
	v_mfma_f32_16x16x32_bf16 v[16:19], v[156:159], v[198:201], v[16:19]
	v_mfma_f32_16x16x32_bf16 v[8:11], v[164:167], v[198:201], v[8:11]
	v_mfma_f32_16x16x32_bf16 v[4:7], v[156:159], v[206:209], v[4:7]
	v_mfma_f32_16x16x32_bf16 v[0:3], v[164:167], v[206:209], v[0:3]
	s_setprio 0
	s_setprio 1
	v_mfma_f32_16x16x32_bf16 v[48:51], v[160:163], v[186:189], v[48:51]
	v_mfma_f32_16x16x32_bf16 v[40:43], v[168:171], v[186:189], v[40:43]
	v_mfma_f32_16x16x32_bf16 v[32:35], v[160:163], v[194:197], v[32:35]
	v_mfma_f32_16x16x32_bf16 v[24:27], v[168:171], v[194:197], v[24:27]
	v_mfma_f32_16x16x32_bf16 v[16:19], v[160:163], v[202:205], v[16:19]
	v_mfma_f32_16x16x32_bf16 v[8:11], v[168:171], v[202:205], v[8:11]
	v_mfma_f32_16x16x32_bf16 v[4:7], v[160:163], v[210:213], v[4:7]
	v_mfma_f32_16x16x32_bf16 v[0:3], v[168:171], v[210:213], v[0:3]
	s_barrier
	s_setprio 0
	s_add_i32 s44, s44, 2
	s_add_u32 s42, s42, 0x100
	s_addc_u32 s43, s43, 0
	s_add_u32 s18, s18, 0x100
	s_addc_u32 s19, s19, 0
	s_cmp_gt_u32 s44, 29
	s_cbranch_scc0 .LBB0_474
	s_and_b64 vcc, exec, s[6:7]
	s_movk_i32 s22, 0x1000
	s_cbranch_vccz .LBB0_477
	s_barrier

.LBB0_490:
	s_add_u32 s28, s6, 0xfff80080
	s_addc_u32 s29, s7, -1
	s_add_i32 s52, 0, 0x10000
	s_cmp_eq_u32 s51, 28
	s_cselect_b32 s31, s23, s29
	s_cselect_b32 s30, s47, s28
	s_cselect_b32 s29, s21, s50
	s_cselect_b32 s28, s48, s49
	s_add_i32 s54, 0, 0x14000
	v_add_u32_e32 v140, s52, v187
	s_waitcnt lgkmcnt(0)
	v_add_u32_e32 v168, s54, v187
	ds_read_b128 v[128:131], v140
	ds_read_b128 v[132:135], v140 offset:1024
	ds_read_b128 v[136:139], v140 offset:2048
	ds_read_b128 v[140:143], v140 offset:3072
	ds_read_b128 v[156:159], v168
	ds_read_b128 v[160:163], v168 offset:1024
	ds_read_b128 v[164:167], v168 offset:2048
	ds_read_b128 v[168:171], v168 offset:3072
	v_lshl_add_u64 v[172:173], s[6:7], 0, v[154:155]
	s_add_i32 m0, s39, 0xc000
	ds_read_b128 v[190:193], v189
	ds_read_b128 v[194:197], v189 offset:1024
	ds_read_b128 v[198:201], v189 offset:2048
	ds_read_b128 v[202:205], v189 offset:3072
	ds_read_b128 v[206:209], v189 offset:4096
	ds_read_b128 v[210:213], v189 offset:5120
	ds_read_b128 v[214:217], v189 offset:6144
	ds_read_b128 v[236:239], v189 offset:7168
	global_load_lds_dwordx4 v[172:173], off
	v_lshl_add_u64 v[172:173], s[6:7], 0, v[152:153]
	s_add_i32 m0, s39, 0xe000
	s_nop 0
	global_load_lds_dwordx4 v[172:173], off
	s_waitcnt vmcnt(8)
	s_waitcnt lgkmcnt(0)
	s_setprio 1
	s_barrier
	v_mfma_f32_16x16x32_bf16 v[124:127], v[128:131], v[190:193], v[124:127]
	v_mfma_f32_16x16x32_bf16 v[120:123], v[136:139], v[190:193], v[120:123]
	v_mfma_f32_16x16x32_bf16 v[108:111], v[128:131], v[198:201], v[108:111]
	v_mfma_f32_16x16x32_bf16 v[104:107], v[136:139], v[198:201], v[104:107]
	v_mfma_f32_16x16x32_bf16 v[92:95], v[128:131], v[206:209], v[92:95]
	v_mfma_f32_16x16x32_bf16 v[88:91], v[136:139], v[206:209], v[88:91]
	v_mfma_f32_16x16x32_bf16 v[76:79], v[128:131], v[214:217], v[76:79]
	v_mfma_f32_16x16x32_bf16 v[72:75], v[136:139], v[214:217], v[72:75]
	s_setprio 0
	s_setprio 1
	v_mfma_f32_16x16x32_bf16 v[124:127], v[132:135], v[194:197], v[124:127]
	v_mfma_f32_16x16x32_bf16 v[120:123], v[140:143], v[194:197], v[120:123]
	v_mfma_f32_16x16x32_bf16 v[108:111], v[132:135], v[202:205], v[108:111]
	v_mfma_f32_16x16x32_bf16 v[104:107], v[140:143], v[202:205], v[104:107]
	v_mfma_f32_16x16x32_bf16 v[92:95], v[132:135], v[210:213], v[92:95]
	v_mfma_f32_16x16x32_bf16 v[88:91], v[140:143], v[210:213], v[88:91]
	v_mfma_f32_16x16x32_bf16 v[76:79], v[132:135], v[236:239], v[76:79]
	v_mfma_f32_16x16x32_bf16 v[72:75], v[140:143], v[236:239], v[72:75]
	s_setprio 0
	s_setprio 1
	v_mfma_f32_16x16x32_bf16 v[116:119], v[156:159], v[190:193], v[116:119]
	v_mfma_f32_16x16x32_bf16 v[112:115], v[164:167], v[190:193], v[112:115]
	v_mfma_f32_16x16x32_bf16 v[100:103], v[156:159], v[198:201], v[100:103]
	v_mfma_f32_16x16x32_bf16 v[96:99], v[164:167], v[198:201], v[96:99]
	v_mfma_f32_16x16x32_bf16 v[84:87], v[156:159], v[206:209], v[84:87]
	v_mfma_f32_16x16x32_bf16 v[80:83], v[164:167], v[206:209], v[80:83]
	v_mfma_f32_16x16x32_bf16 v[68:71], v[156:159], v[214:217], v[68:71]
	v_mfma_f32_16x16x32_bf16 v[64:67], v[164:167], v[214:217], v[64:67]
	s_setprio 0
	s_setprio 1
	v_mfma_f32_16x16x32_bf16 v[116:119], v[160:163], v[194:197], v[116:119]
	v_mfma_f32_16x16x32_bf16 v[112:115], v[168:171], v[194:197], v[112:115]
	v_mfma_f32_16x16x32_bf16 v[100:103], v[160:163], v[202:205], v[100:103]
	v_mfma_f32_16x16x32_bf16 v[96:99], v[168:171], v[202:205], v[96:99]
	v_mfma_f32_16x16x32_bf16 v[84:87], v[160:163], v[210:213], v[84:87]
	v_mfma_f32_16x16x32_bf16 v[80:83], v[168:171], v[210:213], v[80:83]
	v_mfma_f32_16x16x32_bf16 v[68:71], v[160:163], v[236:239], v[68:71]
	v_mfma_f32_16x16x32_bf16 v[64:67], v[168:171], v[236:239], v[64:67]
	s_barrier
	s_setprio 0
	s_add_i32 s52, s52, s38
	v_lshl_add_u64 v[172:173], s[28:29], 0, v[146:147]
	s_mov_b32 m0, s52
	ds_read_b128 v[190:193], v189 offset:16384
	ds_read_b128 v[194:197], v189 offset:17408
	ds_read_b128 v[198:201], v189 offset:18432
	ds_read_b128 v[202:205], v189 offset:19456
	ds_read_b128 v[206:209], v189 offset:20480
	ds_read_b128 v[210:213], v189 offset:21504
	ds_read_b128 v[214:217], v189 offset:22528
	ds_read_b128 v[236:239], v189 offset:23552
	global_load_lds_dwordx4 v[172:173], off
	s_add_i32 m0, s52, 0x2000
	s_add_u32 s52, s28, 0x80000
	v_lshl_add_u64 v[218:219], s[28:29], 0, v[144:145]
	s_addc_u32 s53, s29, 0
	s_add_i32 s54, s54, s38
	global_load_lds_dwordx4 v[218:219], off
	v_lshl_add_u64 v[228:229], s[52:53], 0, v[146:147]
	s_mov_b32 m0, s54
	v_lshl_add_u64 v[230:231], s[30:31], 0, v[144:145]
	global_load_lds_dwordx4 v[228:229], off
	v_lshl_add_u64 v[228:229], s[52:53], 0, v[144:145]
	s_add_i32 m0, s54, 0x2000
	s_nop 0
	global_load_lds_dwordx4 v[228:229], off
	v_lshl_add_u64 v[228:229], s[30:31], 0, v[146:147]
	s_mov_b32 m0, s39
	s_nop 0
	global_load_lds_dwordx4 v[228:229], off
	s_mov_b32 m0, s40
	s_nop 0
	global_load_lds_dwordx4 v[230:231], off
	s_waitcnt vmcnt(8)
	s_waitcnt lgkmcnt(0)
	s_setprio 1
	s_barrier
	v_mfma_f32_16x16x32_bf16 v[60:63], v[128:131], v[190:193], v[60:63]
	v_mfma_f32_16x16x32_bf16 v[56:59], v[136:139], v[190:193], v[56:59]
	v_mfma_f32_16x16x32_bf16 v[44:47], v[128:131], v[198:201], v[44:47]
	v_mfma_f32_16x16x32_bf16 v[40:43], v[136:139], v[198:201], v[40:43]
	v_mfma_f32_16x16x32_bf16 v[28:31], v[128:131], v[206:209], v[28:31]
	v_mfma_f32_16x16x32_bf16 v[24:27], v[136:139], v[206:209], v[24:27]
	v_mfma_f32_16x16x32_bf16 v[12:15], v[128:131], v[214:217], v[12:15]
	v_mfma_f32_16x16x32_bf16 v[8:11], v[136:139], v[214:217], v[8:11]
	s_setprio 0
	s_setprio 1
	v_mfma_f32_16x16x32_bf16 v[60:63], v[132:135], v[194:197], v[60:63]
	v_mfma_f32_16x16x32_bf16 v[56:59], v[140:143], v[194:197], v[56:59]
	v_mfma_f32_16x16x32_bf16 v[44:47], v[132:135], v[202:205], v[44:47]
	v_mfma_f32_16x16x32_bf16 v[40:43], v[140:143], v[202:205], v[40:43]
	v_mfma_f32_16x16x32_bf16 v[28:31], v[132:135], v[210:213], v[28:31]
	v_mfma_f32_16x16x32_bf16 v[24:27], v[140:143], v[210:213], v[24:27]
	v_mfma_f32_16x16x32_bf16 v[12:15], v[132:135], v[236:239], v[12:15]
	v_mfma_f32_16x16x32_bf16 v[8:11], v[140:143], v[236:239], v[8:11]
	s_setprio 0
	s_setprio 1
	v_mfma_f32_16x16x32_bf16 v[52:55], v[156:159], v[190:193], v[52:55]
	v_mfma_f32_16x16x32_bf16 v[48:51], v[164:167], v[190:193], v[48:51]
	v_mfma_f32_16x16x32_bf16 v[36:39], v[156:159], v[198:201], v[36:39]
	v_mfma_f32_16x16x32_bf16 v[32:35], v[164:167], v[198:201], v[32:35]
	v_mfma_f32_16x16x32_bf16 v[20:23], v[156:159], v[206:209], v[20:23]
	v_mfma_f32_16x16x32_bf16 v[16:19], v[164:167], v[206:209], v[16:19]
	v_mfma_f32_16x16x32_bf16 v[4:7], v[156:159], v[214:217], v[4:7]
	v_mfma_f32_16x16x32_bf16 v[0:3], v[164:167], v[214:217], v[0:3]
	s_setprio 0
	s_setprio 1
	v_mfma_f32_16x16x32_bf16 v[52:55], v[160:163], v[194:197], v[52:55]
	v_mfma_f32_16x16x32_bf16 v[48:51], v[168:171], v[194:197], v[48:51]
	v_mfma_f32_16x16x32_bf16 v[36:39], v[160:163], v[202:205], v[36:39]
	v_mfma_f32_16x16x32_bf16 v[32:35], v[168:171], v[202:205], v[32:35]
	v_mfma_f32_16x16x32_bf16 v[20:23], v[160:163], v[210:213], v[20:23]
	v_mfma_f32_16x16x32_bf16 v[16:19], v[168:171], v[210:213], v[16:19]
	v_mfma_f32_16x16x32_bf16 v[4:7], v[160:163], v[236:239], v[4:7]
	v_mfma_f32_16x16x32_bf16 v[0:3], v[168:171], v[236:239], v[0:3]
	s_barrier
	s_setprio 0
	s_add_i32 s52, 0, 0x18000
	s_add_i32 s53, 0, 0x1c000
	v_add_u32_e32 v140, s52, v187
	v_add_u32_e32 v168, s53, v187
	ds_read_b128 v[128:131], v140
	ds_read_b128 v[132:135], v140 offset:1024
	ds_read_b128 v[136:139], v140 offset:2048
	ds_read_b128 v[140:143], v140 offset:3072
	ds_read_b128 v[156:159], v168
	ds_read_b128 v[160:163], v168 offset:1024
	ds_read_b128 v[164:167], v168 offset:2048
	ds_read_b128 v[168:171], v168 offset:3072
	s_add_u32 s30, s30, 0x80000
	s_addc_u32 s31, s31, 0
	s_mov_b32 m0, s41
	v_lshl_add_u64 v[240:241], s[30:31], 0, v[146:147]
	ds_read_b128 v[190:193], v189 offset:32768
	ds_read_b128 v[194:197], v189 offset:33792
	ds_read_b128 v[198:201], v189 offset:34816
	ds_read_b128 v[202:205], v189 offset:35840
	ds_read_b128 v[206:209], v189 offset:36864
	ds_read_b128 v[210:213], v189 offset:37888
	ds_read_b128 v[214:217], v189 offset:38912
	ds_read_b128 v[236:239], v189 offset:39936
	global_load_lds_dwordx4 v[240:241], off
	v_lshl_add_u64 v[240:241], s[30:31], 0, v[144:145]
	s_mov_b32 m0, s42
	s_nop 0
	global_load_lds_dwordx4 v[240:241], off
	s_waitcnt vmcnt(8)
	s_waitcnt lgkmcnt(0)
	s_setprio 1
	s_barrier
	v_mfma_f32_16x16x32_bf16 v[124:127], v[128:131], v[190:193], v[124:127]
	v_mfma_f32_16x16x32_bf16 v[120:123], v[136:139], v[190:193], v[120:123]
	v_mfma_f32_16x16x32_bf16 v[108:111], v[128:131], v[198:201], v[108:111]
	v_mfma_f32_16x16x32_bf16 v[104:107], v[136:139], v[198:201], v[104:107]
	v_mfma_f32_16x16x32_bf16 v[92:95], v[128:131], v[206:209], v[92:95]
	v_mfma_f32_16x16x32_bf16 v[88:91], v[136:139], v[206:209], v[88:91]
	v_mfma_f32_16x16x32_bf16 v[76:79], v[128:131], v[214:217], v[76:79]
	v_mfma_f32_16x16x32_bf16 v[72:75], v[136:139], v[214:217], v[72:75]
	s_setprio 0
	s_setprio 1
	v_mfma_f32_16x16x32_bf16 v[124:127], v[132:135], v[194:197], v[124:127]
	v_mfma_f32_16x16x32_bf16 v[120:123], v[140:143], v[194:197], v[120:123]
	v_mfma_f32_16x16x32_bf16 v[108:111], v[132:135], v[202:205], v[108:111]
	v_mfma_f32_16x16x32_bf16 v[104:107], v[140:143], v[202:205], v[104:107]
	v_mfma_f32_16x16x32_bf16 v[92:95], v[132:135], v[210:213], v[92:95]
	v_mfma_f32_16x16x32_bf16 v[88:91], v[140:143], v[210:213], v[88:91]
	v_mfma_f32_16x16x32_bf16 v[76:79], v[132:135], v[236:239], v[76:79]
	v_mfma_f32_16x16x32_bf16 v[72:75], v[140:143], v[236:239], v[72:75]
	s_setprio 0
	s_setprio 1
	v_mfma_f32_16x16x32_bf16 v[116:119], v[156:159], v[190:193], v[116:119]
	v_mfma_f32_16x16x32_bf16 v[112:115], v[164:167], v[190:193], v[112:115]
	v_mfma_f32_16x16x32_bf16 v[100:103], v[156:159], v[198:201], v[100:103]
	v_mfma_f32_16x16x32_bf16 v[96:99], v[164:167], v[198:201], v[96:99]
	v_mfma_f32_16x16x32_bf16 v[84:87], v[156:159], v[206:209], v[84:87]
	v_mfma_f32_16x16x32_bf16 v[80:83], v[164:167], v[206:209], v[80:83]
	v_mfma_f32_16x16x32_bf16 v[68:71], v[156:159], v[214:217], v[68:71]
	v_mfma_f32_16x16x32_bf16 v[64:67], v[164:167], v[214:217], v[64:67]
	s_setprio 0
	s_setprio 1
	v_mfma_f32_16x16x32_bf16 v[116:119], v[160:163], v[194:197], v[116:119]
	v_mfma_f32_16x16x32_bf16 v[112:115], v[168:171], v[194:197], v[112:115]
	v_mfma_f32_16x16x32_bf16 v[100:103], v[160:163], v[202:205], v[100:103]
	v_mfma_f32_16x16x32_bf16 v[96:99], v[168:171], v[202:205], v[96:99]
	v_mfma_f32_16x16x32_bf16 v[84:87], v[160:163], v[210:213], v[84:87]
	v_mfma_f32_16x16x32_bf16 v[80:83], v[168:171], v[210:213], v[80:83]
	v_mfma_f32_16x16x32_bf16 v[68:71], v[160:163], v[236:239], v[68:71]
	v_mfma_f32_16x16x32_bf16 v[64:67], v[168:171], v[236:239], v[64:67]
	s_barrier
	s_setprio 0
	s_add_i32 s30, s52, s38
	v_lshl_add_u64 v[172:173], v[172:173], 0, s[0:1]
	s_mov_b32 m0, s30
	ds_read_b128 v[190:193], v189 offset:49152
	ds_read_b128 v[194:197], v189 offset:50176
	ds_read_b128 v[198:201], v189 offset:51200
	ds_read_b128 v[202:205], v189 offset:52224
	ds_read_b128 v[206:209], v189 offset:53248
	ds_read_b128 v[210:213], v189 offset:54272
	ds_read_b128 v[214:217], v189 offset:55296
	ds_read_b128 v[236:239], v189 offset:56320
	global_load_lds_dwordx4 v[172:173], off
	s_add_i32 m0, s30, 0x2000
	s_add_u32 s28, s28, 0x80080
	v_lshl_add_u64 v[172:173], v[218:219], 0, s[0:1]
	s_addc_u32 s29, s29, 0
	s_add_i32 s30, s53, s38
	global_load_lds_dwordx4 v[172:173], off
	v_lshl_add_u64 v[172:173], s[28:29], 0, v[146:147]
	s_mov_b32 m0, s30
	s_nop 0
	global_load_lds_dwordx4 v[172:173], off
	v_lshl_add_u64 v[172:173], s[28:29], 0, v[144:145]
	s_add_i32 m0, s30, 0x2000
	s_nop 0
	global_load_lds_dwordx4 v[172:173], off
	v_lshl_add_u64 v[172:173], v[228:229], 0, s[0:1]
	s_mov_b32 m0, s44
	s_nop 0
	global_load_lds_dwordx4 v[172:173], off
	v_lshl_add_u64 v[172:173], v[230:231], 0, s[0:1]
	s_mov_b32 m0, s45
	s_nop 0
	global_load_lds_dwordx4 v[172:173], off
	s_waitcnt vmcnt(8)
	s_waitcnt lgkmcnt(0)
	s_setprio 1
	s_barrier
	v_mfma_f32_16x16x32_bf16 v[60:63], v[128:131], v[190:193], v[60:63]
	v_mfma_f32_16x16x32_bf16 v[56:59], v[136:139], v[190:193], v[56:59]
	v_mfma_f32_16x16x32_bf16 v[44:47], v[128:131], v[198:201], v[44:47]
	v_mfma_f32_16x16x32_bf16 v[40:43], v[136:139], v[198:201], v[40:43]
	v_mfma_f32_16x16x32_bf16 v[28:31], v[128:131], v[206:209], v[28:31]
	v_mfma_f32_16x16x32_bf16 v[24:27], v[136:139], v[206:209], v[24:27]
	v_mfma_f32_16x16x32_bf16 v[12:15], v[128:131], v[214:217], v[12:15]
	v_mfma_f32_16x16x32_bf16 v[8:11], v[136:139], v[214:217], v[8:11]
	s_setprio 0
	s_setprio 1
	v_mfma_f32_16x16x32_bf16 v[60:63], v[132:135], v[194:197], v[60:63]
	v_mfma_f32_16x16x32_bf16 v[56:59], v[140:143], v[194:197], v[56:59]
	v_mfma_f32_16x16x32_bf16 v[44:47], v[132:135], v[202:205], v[44:47]
	v_mfma_f32_16x16x32_bf16 v[40:43], v[140:143], v[202:205], v[40:43]
	v_mfma_f32_16x16x32_bf16 v[28:31], v[132:135], v[210:213], v[28:31]
	v_mfma_f32_16x16x32_bf16 v[24:27], v[140:143], v[210:213], v[24:27]
	v_mfma_f32_16x16x32_bf16 v[12:15], v[132:135], v[236:239], v[12:15]
	v_mfma_f32_16x16x32_bf16 v[8:11], v[140:143], v[236:239], v[8:11]
	s_setprio 0
	s_setprio 1
	v_mfma_f32_16x16x32_bf16 v[52:55], v[156:159], v[190:193], v[52:55]
	v_mfma_f32_16x16x32_bf16 v[48:51], v[164:167], v[190:193], v[48:51]
	v_mfma_f32_16x16x32_bf16 v[36:39], v[156:159], v[198:201], v[36:39]
	v_mfma_f32_16x16x32_bf16 v[32:35], v[164:167], v[198:201], v[32:35]
	v_mfma_f32_16x16x32_bf16 v[20:23], v[156:159], v[206:209], v[20:23]
	v_mfma_f32_16x16x32_bf16 v[16:19], v[164:167], v[206:209], v[16:19]
	v_mfma_f32_16x16x32_bf16 v[4:7], v[156:159], v[214:217], v[4:7]
	v_mfma_f32_16x16x32_bf16 v[0:3], v[164:167], v[214:217], v[0:3]
	s_setprio 0
	s_setprio 1
	v_mfma_f32_16x16x32_bf16 v[52:55], v[160:163], v[194:197], v[52:55]
	v_mfma_f32_16x16x32_bf16 v[48:51], v[168:171], v[194:197], v[48:51]
	v_mfma_f32_16x16x32_bf16 v[36:39], v[160:163], v[202:205], v[36:39]
	v_mfma_f32_16x16x32_bf16 v[32:35], v[168:171], v[202:205], v[32:35]
	v_mfma_f32_16x16x32_bf16 v[20:23], v[160:163], v[210:213], v[20:23]
	v_mfma_f32_16x16x32_bf16 v[16:19], v[168:171], v[210:213], v[16:19]
	v_mfma_f32_16x16x32_bf16 v[4:7], v[160:163], v[236:239], v[4:7]
	v_mfma_f32_16x16x32_bf16 v[0:3], v[168:171], v[236:239], v[0:3]
	s_barrier
	s_setprio 0
	s_add_i32 s51, s51, 2
	s_add_u32 s49, s49, 0x100
	s_addc_u32 s50, s50, 0
	s_add_u32 s6, s6, 0x100
	s_addc_u32 s7, s7, 0
	s_cmp_gt_u32 s51, 29
	s_cbranch_scc0 .LBB0_490
	s_and_b64 vcc, exec, s[12:13]
	s_cbranch_vccz .LBB0_493
	s_barrier
